# Bout reuses Bst gains/skip loads (no vmcnt wait), unorm_chunk second-row loads hoisted beside the first row's
# speedup vs baseline: 1.0189x; 1.0024x over previous
; __device__ __forceinline__ void s5_gen(LAS unsigned char* lds, const S5In P, int g, int q, bf16_t* Bst, bf16_t* Bout, const int tid) {
;     ...
;     { const int di = tid >> 8, k = (tid >> 4) & 15, chb = (tid >> 2) & 3, c2b = tid & 3;
;       float acc[4][4];
; #pragma unroll
;       for (int a_ = 0; a_ < 4; ++a_)
; #pragma unroll
;           for (int b_ = 0; b_ < 4; ++b_) acc[a_][b_] = 0.f;
;       for (int p = 0; p < 64; ++p) { const f32x2v w = pw[(di * 64 + p) * 17 + k]; float zr[4], zi[4];
; #pragma unroll
;           for (int b_ = 0; b_ < 4; ++b_) { const f32x2v b = bb[(di * 64 + p) * 16 + 4 * c2b + b_]; zr[b_] = w.x * b.x - w.y * b.y; zi[b_] = w.x * b.y + w.y * b.x; }
; #pragma unroll
;           for (int a_ = 0; a_ < 4; ++a_) { const f32x2v C = cc[(di * 16 + 4 * chb + a_) * 64 + p];
; #pragma unroll
;               for (int b_ = 0; b_ < 4; ++b_) acc[a_][b_] += C.x * zr[b_] - C.y * zi[b_]; } }
; #pragma unroll
;       for (int a_ = 0; a_ < 4; ++a_)
; #pragma unroll
;           for (int b_ = 0; b_ < 4; ++b_) kt[((di * 16 + k) * 16 + 4 * chb + a_) * 16 + 4 * c2b + b_] = acc[a_][b_]; }
.LBB0_197:
	s_or_b64 exec, exec, s[28:29]
	v_mov_b32_e32 v0, 0
	s_mov_b32 s17, 0
	v_mov_b32_e32 v43, v38
	v_mov_b32_e32 v44, v37
	v_mov_b32_e32 v1, v0
	v_mov_b32_e32 v2, v0
	v_mov_b32_e32 v3, v0
	v_mov_b32_e32 v12, v0
	v_mov_b32_e32 v13, v0
	v_mov_b32_e32 v14, v0
	v_mov_b32_e32 v15, v0
	v_mov_b32_e32 v8, v0
	v_mov_b32_e32 v9, v0
	v_mov_b32_e32 v10, v0
	v_mov_b32_e32 v11, v0
	v_mov_b32_e32 v4, v0
	v_mov_b32_e32 v5, v0
	v_mov_b32_e32 v6, v0
	v_mov_b32_e32 v7, v0
	s_waitcnt lgkmcnt(0)
	s_barrier
	v_mbcnt_lo_u32_b32 v43, -1, 0
	v_mbcnt_hi_u32_b32 v43, -1, v43
	v_and_b32_e32 v44, 15, v43
	v_lshrrev_b32_e32 v45, 4, v43
	v_lshrrev_b32_e32 v32, 6, v66
	s_nop 0
	v_readfirstlane_b32 s42, v32
	s_nop 3
	s_lshr_b32 s43, s42, 2
	s_and_b32 s44, s42, 3
	s_lshl_b32 s44, s44, 2
	s_lshl_b32 s45, s43, 6
	v_add_u32_e32 v32, s45, v45
	v_lshlrev_b32_e32 v200, 7, v32
	v_lshl_add_u32 v200, v44, 3, v200
	v_add_u32_e32 v200, 0x4400, v200
	v_mul_u32_u24_e32 v201, 0x88, v32
	s_lshl_b32 s46, s44, 3
	v_add_u32_e32 v201, s46, v201
	s_lshl_b32 s46, s43, 4
	v_add_u32_e32 v32, s46, v44
	v_lshlrev_b32_e32 v202, 9, v32
	v_lshl_add_u32 v202, v45, 3, v202
	v_add_u32_e32 v202, 0x8400, v202
	s_add_i32 s46, s46, s44
	s_lshl_b32 s46, s46, 10
	v_lshlrev_b32_e32 v203, 8, v45
	v_lshl_add_u32 v203, v44, 2, v203
	v_add_u32_e32 v203, s46, v203
	v_add_u32_e32 v203, 0xc400, v203
	ds_read_b64 v[132:133], v200
	ds_read_b64 v[134:135], v200 offset:512
	ds_read_b64 v[136:137], v200 offset:1024
	ds_read_b64 v[138:139], v200 offset:1536
	ds_read_b64 v[140:141], v200 offset:2048
	ds_read_b64 v[142:143], v200 offset:2560
	ds_read_b64 v[144:145], v200 offset:3072
	ds_read_b64 v[146:147], v200 offset:3584
	ds_read_b64 v[148:149], v200 offset:4096
	ds_read_b64 v[150:151], v200 offset:4608
	ds_read_b64 v[152:153], v200 offset:5120
	ds_read_b64 v[154:155], v200 offset:5632
	ds_read_b64 v[156:157], v200 offset:6144
	ds_read_b64 v[158:159], v200 offset:6656
	ds_read_b64 v[160:161], v200 offset:7168
	ds_read_b64 v[162:163], v200 offset:7680
	ds_read_b64 v[164:165], v202
	ds_read_b64 v[166:167], v202 offset:32
	ds_read_b64 v[168:169], v202 offset:64
	ds_read_b64 v[170:171], v202 offset:96
	ds_read_b64 v[172:173], v202 offset:128
	ds_read_b64 v[174:175], v202 offset:160
	ds_read_b64 v[176:177], v202 offset:192
	ds_read_b64 v[178:179], v202 offset:224
	ds_read_b64 v[180:181], v202 offset:256
	ds_read_b64 v[182:183], v202 offset:288
	ds_read_b64 v[184:185], v202 offset:320
	ds_read_b64 v[186:187], v202 offset:352
	ds_read_b64 v[188:189], v202 offset:384
	ds_read_b64 v[190:191], v202 offset:416
	ds_read_b64 v[192:193], v202 offset:448
	ds_read_b64 v[194:195], v202 offset:480
	ds_read_b64 v[0:1], v201
	ds_read_b64 v[2:3], v201 offset:8
	ds_read_b64 v[4:5], v201 offset:16
	ds_read_b64 v[6:7], v201 offset:24
	ds_read_b64 v[8:9], v201 offset:544
	ds_read_b64 v[10:11], v201 offset:552
	ds_read_b64 v[12:13], v201 offset:560
	ds_read_b64 v[14:15], v201 offset:568
	s_waitcnt lgkmcnt(4)
	v_mul_f32_e32 v16, v165, v1
	v_mul_f32_e32 v17, v165, v0
	v_fma_f32 v16, v164, v0, -v16
	v_fma_f32 v17, -v164, v1, -v17
	v_mul_f32_e32 v18, v165, v3
	v_mul_f32_e32 v19, v165, v2
	v_fma_f32 v18, v164, v2, -v18
	v_fma_f32 v19, -v164, v3, -v19
	v_mul_f32_e32 v20, v165, v5
	v_mul_f32_e32 v21, v165, v4
	v_fma_f32 v20, v164, v4, -v20
	v_fma_f32 v21, -v164, v5, -v21
	v_mul_f32_e32 v22, v165, v7
	v_mul_f32_e32 v23, v165, v6
	v_fma_f32 v22, v164, v6, -v22
	v_fma_f32 v23, -v164, v7, -v23
	s_nop 1
	v_mfma_f32_16x16x4_f32 v[48:51], v16, v132, 0
	v_mfma_f32_16x16x4_f32 v[52:55], v18, v132, 0
	v_mfma_f32_16x16x4_f32 v[56:59], v20, v132, 0
	v_mfma_f32_16x16x4_f32 v[196:199], v22, v132, 0
	v_mfma_f32_16x16x4_f32 v[48:51], v17, v133, v[48:51]
	v_mfma_f32_16x16x4_f32 v[52:55], v19, v133, v[52:55]
	v_mfma_f32_16x16x4_f32 v[56:59], v21, v133, v[56:59]
	v_mfma_f32_16x16x4_f32 v[196:199], v23, v133, v[196:199]
	ds_read_b64 v[0:1], v201 offset:1088
	ds_read_b64 v[2:3], v201 offset:1096
	ds_read_b64 v[4:5], v201 offset:1104
	ds_read_b64 v[6:7], v201 offset:1112
	s_waitcnt lgkmcnt(4)
	v_mul_f32_e32 v16, v167, v9
	v_mul_f32_e32 v17, v167, v8
	v_fma_f32 v16, v166, v8, -v16
	v_fma_f32 v17, -v166, v9, -v17
	v_mul_f32_e32 v18, v167, v11
	v_mul_f32_e32 v19, v167, v10
	v_fma_f32 v18, v166, v10, -v18
	v_fma_f32 v19, -v166, v11, -v19
	v_mul_f32_e32 v20, v167, v13
	v_mul_f32_e32 v21, v167, v12
	v_fma_f32 v20, v166, v12, -v20
	v_fma_f32 v21, -v166, v13, -v21
	v_mul_f32_e32 v22, v167, v15
	v_mul_f32_e32 v23, v167, v14
	v_fma_f32 v22, v166, v14, -v22
	v_fma_f32 v23, -v166, v15, -v23
	s_nop 1
	v_mfma_f32_16x16x4_f32 v[48:51], v16, v134, v[48:51]
	v_mfma_f32_16x16x4_f32 v[52:55], v18, v134, v[52:55]
	v_mfma_f32_16x16x4_f32 v[56:59], v20, v134, v[56:59]
	v_mfma_f32_16x16x4_f32 v[196:199], v22, v134, v[196:199]
	v_mfma_f32_16x16x4_f32 v[48:51], v17, v135, v[48:51]
	v_mfma_f32_16x16x4_f32 v[52:55], v19, v135, v[52:55]
	v_mfma_f32_16x16x4_f32 v[56:59], v21, v135, v[56:59]
	v_mfma_f32_16x16x4_f32 v[196:199], v23, v135, v[196:199]
	ds_read_b64 v[8:9], v201 offset:1632
	ds_read_b64 v[10:11], v201 offset:1640
	ds_read_b64 v[12:13], v201 offset:1648
	ds_read_b64 v[14:15], v201 offset:1656
	s_waitcnt lgkmcnt(4)
; __device__ __forceinline__ void s5_gen(LAS unsigned char* lds, const S5In P, int g, int q, bf16_t* Bst, bf16_t* Bout, const int tid) {
;     ...
;       for (int p = 0; p < 64; ++p) { const f32x2v w = pw[(di * 64 + p) * 17 + k]; float zr[4], zi[4];
; #pragma unroll
;           for (int b_ = 0; b_ < 4; ++b_) { const f32x2v b = bb[(di * 64 + p) * 16 + 4 * c2b + b_]; zr[b_] = w.x * b.x - w.y * b.y; zi[b_] = w.x * b.y + w.y * b.x; }
; #pragma unroll
;           for (int a_ = 0; a_ < 4; ++a_) { const f32x2v C = cc[(di * 16 + 4 * chb + a_) * 64 + p];
; #pragma unroll
;               for (int b_ = 0; b_ < 4; ++b_) acc[a_][b_] += C.x * zr[b_] - C.y * zi[b_]; } }
	v_mul_f32_e32 v16, v169, v1
	v_mul_f32_e32 v17, v169, v0
	v_fma_f32 v16, v168, v0, -v16
	v_fma_f32 v17, -v168, v1, -v17
	v_mul_f32_e32 v18, v169, v3
	v_mul_f32_e32 v19, v169, v2
	v_fma_f32 v18, v168, v2, -v18
	v_fma_f32 v19, -v168, v3, -v19
	v_mul_f32_e32 v20, v169, v5
	v_mul_f32_e32 v21, v169, v4
	v_fma_f32 v20, v168, v4, -v20
	v_fma_f32 v21, -v168, v5, -v21
	v_mul_f32_e32 v22, v169, v7
	v_mul_f32_e32 v23, v169, v6
	v_fma_f32 v22, v168, v6, -v22
	v_fma_f32 v23, -v168, v7, -v23
	s_nop 1
	v_mfma_f32_16x16x4_f32 v[48:51], v16, v136, v[48:51]
	v_mfma_f32_16x16x4_f32 v[52:55], v18, v136, v[52:55]
	v_mfma_f32_16x16x4_f32 v[56:59], v20, v136, v[56:59]
	v_mfma_f32_16x16x4_f32 v[196:199], v22, v136, v[196:199]
	v_mfma_f32_16x16x4_f32 v[48:51], v17, v137, v[48:51]
	v_mfma_f32_16x16x4_f32 v[52:55], v19, v137, v[52:55]
	v_mfma_f32_16x16x4_f32 v[56:59], v21, v137, v[56:59]
	v_mfma_f32_16x16x4_f32 v[196:199], v23, v137, v[196:199]
	ds_read_b64 v[0:1], v201 offset:2176
	ds_read_b64 v[2:3], v201 offset:2184
	ds_read_b64 v[4:5], v201 offset:2192
	ds_read_b64 v[6:7], v201 offset:2200
	s_waitcnt lgkmcnt(4)
	v_mul_f32_e32 v16, v171, v9
	v_mul_f32_e32 v17, v171, v8
	v_fma_f32 v16, v170, v8, -v16
	v_fma_f32 v17, -v170, v9, -v17
	v_mul_f32_e32 v18, v171, v11
	v_mul_f32_e32 v19, v171, v10
	v_fma_f32 v18, v170, v10, -v18
	v_fma_f32 v19, -v170, v11, -v19
	v_mul_f32_e32 v20, v171, v13
	v_mul_f32_e32 v21, v171, v12
	v_fma_f32 v20, v170, v12, -v20
	v_fma_f32 v21, -v170, v13, -v21
	v_mul_f32_e32 v22, v171, v15
	v_mul_f32_e32 v23, v171, v14
	v_fma_f32 v22, v170, v14, -v22
	v_fma_f32 v23, -v170, v15, -v23
	s_nop 1
	v_mfma_f32_16x16x4_f32 v[48:51], v16, v138, v[48:51]
	v_mfma_f32_16x16x4_f32 v[52:55], v18, v138, v[52:55]
	v_mfma_f32_16x16x4_f32 v[56:59], v20, v138, v[56:59]
	v_mfma_f32_16x16x4_f32 v[196:199], v22, v138, v[196:199]
	v_mfma_f32_16x16x4_f32 v[48:51], v17, v139, v[48:51]
	v_mfma_f32_16x16x4_f32 v[52:55], v19, v139, v[52:55]
	v_mfma_f32_16x16x4_f32 v[56:59], v21, v139, v[56:59]
	v_mfma_f32_16x16x4_f32 v[196:199], v23, v139, v[196:199]
	ds_read_b64 v[8:9], v201 offset:2720
	ds_read_b64 v[10:11], v201 offset:2728
	ds_read_b64 v[12:13], v201 offset:2736
	ds_read_b64 v[14:15], v201 offset:2744
	s_waitcnt lgkmcnt(4)
	v_mul_f32_e32 v16, v173, v1
	v_mul_f32_e32 v17, v173, v0
	v_fma_f32 v16, v172, v0, -v16
	v_fma_f32 v17, -v172, v1, -v17
	v_mul_f32_e32 v18, v173, v3
	v_mul_f32_e32 v19, v173, v2
	v_fma_f32 v18, v172, v2, -v18
	v_fma_f32 v19, -v172, v3, -v19
	v_mul_f32_e32 v20, v173, v5
	v_mul_f32_e32 v21, v173, v4
	v_fma_f32 v20, v172, v4, -v20
	v_fma_f32 v21, -v172, v5, -v21
	v_mul_f32_e32 v22, v173, v7
	v_mul_f32_e32 v23, v173, v6
	v_fma_f32 v22, v172, v6, -v22
	v_fma_f32 v23, -v172, v7, -v23
	s_nop 1
	v_mfma_f32_16x16x4_f32 v[48:51], v16, v140, v[48:51]
	v_mfma_f32_16x16x4_f32 v[52:55], v18, v140, v[52:55]
	v_mfma_f32_16x16x4_f32 v[56:59], v20, v140, v[56:59]
	v_mfma_f32_16x16x4_f32 v[196:199], v22, v140, v[196:199]
	v_mfma_f32_16x16x4_f32 v[48:51], v17, v141, v[48:51]
	v_mfma_f32_16x16x4_f32 v[52:55], v19, v141, v[52:55]
	v_mfma_f32_16x16x4_f32 v[56:59], v21, v141, v[56:59]
	v_mfma_f32_16x16x4_f32 v[196:199], v23, v141, v[196:199]
	ds_read_b64 v[0:1], v201 offset:3264
	ds_read_b64 v[2:3], v201 offset:3272
	ds_read_b64 v[4:5], v201 offset:3280
	ds_read_b64 v[6:7], v201 offset:3288
	s_waitcnt lgkmcnt(4)
	v_mul_f32_e32 v16, v175, v9
	v_mul_f32_e32 v17, v175, v8
	v_fma_f32 v16, v174, v8, -v16
	v_fma_f32 v17, -v174, v9, -v17
	v_mul_f32_e32 v18, v175, v11
	v_mul_f32_e32 v19, v175, v10
	v_fma_f32 v18, v174, v10, -v18
	v_fma_f32 v19, -v174, v11, -v19
	v_mul_f32_e32 v20, v175, v13
	v_mul_f32_e32 v21, v175, v12
	v_fma_f32 v20, v174, v12, -v20
	v_fma_f32 v21, -v174, v13, -v21
	v_mul_f32_e32 v22, v175, v15
	v_mul_f32_e32 v23, v175, v14
	v_fma_f32 v22, v174, v14, -v22
	v_fma_f32 v23, -v174, v15, -v23
	s_nop 1
	v_mfma_f32_16x16x4_f32 v[48:51], v16, v142, v[48:51]
	v_mfma_f32_16x16x4_f32 v[52:55], v18, v142, v[52:55]
	v_mfma_f32_16x16x4_f32 v[56:59], v20, v142, v[56:59]
	v_mfma_f32_16x16x4_f32 v[196:199], v22, v142, v[196:199]
	v_mfma_f32_16x16x4_f32 v[48:51], v17, v143, v[48:51]
	v_mfma_f32_16x16x4_f32 v[52:55], v19, v143, v[52:55]
	v_mfma_f32_16x16x4_f32 v[56:59], v21, v143, v[56:59]
	v_mfma_f32_16x16x4_f32 v[196:199], v23, v143, v[196:199]
	ds_read_b64 v[8:9], v201 offset:3808
	ds_read_b64 v[10:11], v201 offset:3816
	ds_read_b64 v[12:13], v201 offset:3824
	ds_read_b64 v[14:15], v201 offset:3832
	s_waitcnt lgkmcnt(4)
	v_mul_f32_e32 v16, v177, v1
	v_mul_f32_e32 v17, v177, v0
	v_fma_f32 v16, v176, v0, -v16
	v_fma_f32 v17, -v176, v1, -v17
	v_mul_f32_e32 v18, v177, v3
	v_mul_f32_e32 v19, v177, v2
	v_fma_f32 v18, v176, v2, -v18
	v_fma_f32 v19, -v176, v3, -v19
	v_mul_f32_e32 v20, v177, v5
	v_mul_f32_e32 v21, v177, v4
	v_fma_f32 v20, v176, v4, -v20
	v_fma_f32 v21, -v176, v5, -v21
	v_mul_f32_e32 v22, v177, v7
	v_mul_f32_e32 v23, v177, v6
	v_fma_f32 v22, v176, v6, -v22
	v_fma_f32 v23, -v176, v7, -v23
	s_nop 1
	v_mfma_f32_16x16x4_f32 v[48:51], v16, v144, v[48:51]
	v_mfma_f32_16x16x4_f32 v[52:55], v18, v144, v[52:55]
	v_mfma_f32_16x16x4_f32 v[56:59], v20, v144, v[56:59]
	v_mfma_f32_16x16x4_f32 v[196:199], v22, v144, v[196:199]
	v_mfma_f32_16x16x4_f32 v[48:51], v17, v145, v[48:51]
	v_mfma_f32_16x16x4_f32 v[52:55], v19, v145, v[52:55]
	v_mfma_f32_16x16x4_f32 v[56:59], v21, v145, v[56:59]
	v_mfma_f32_16x16x4_f32 v[196:199], v23, v145, v[196:199]
	ds_read_b64 v[0:1], v201 offset:4352
	ds_read_b64 v[2:3], v201 offset:4360
	ds_read_b64 v[4:5], v201 offset:4368
	ds_read_b64 v[6:7], v201 offset:4376
	s_waitcnt lgkmcnt(4)
; __device__ __forceinline__ void s5_gen(LAS unsigned char* lds, const S5In P, int g, int q, bf16_t* Bst, bf16_t* Bout, const int tid) {
;     ...
;       for (int p = 0; p < 64; ++p) { const f32x2v w = pw[(di * 64 + p) * 17 + k]; float zr[4], zi[4];
; #pragma unroll
;           for (int b_ = 0; b_ < 4; ++b_) { const f32x2v b = bb[(di * 64 + p) * 16 + 4 * c2b + b_]; zr[b_] = w.x * b.x - w.y * b.y; zi[b_] = w.x * b.y + w.y * b.x; }
; #pragma unroll
;           for (int a_ = 0; a_ < 4; ++a_) { const f32x2v C = cc[(di * 16 + 4 * chb + a_) * 64 + p];
; #pragma unroll
;               for (int b_ = 0; b_ < 4; ++b_) acc[a_][b_] += C.x * zr[b_] - C.y * zi[b_]; } }
	v_mul_f32_e32 v16, v179, v9
	v_mul_f32_e32 v17, v179, v8
	v_fma_f32 v16, v178, v8, -v16
	v_fma_f32 v17, -v178, v9, -v17
	v_mul_f32_e32 v18, v179, v11
	v_mul_f32_e32 v19, v179, v10
	v_fma_f32 v18, v178, v10, -v18
	v_fma_f32 v19, -v178, v11, -v19
	v_mul_f32_e32 v20, v179, v13
	v_mul_f32_e32 v21, v179, v12
	v_fma_f32 v20, v178, v12, -v20
	v_fma_f32 v21, -v178, v13, -v21
	v_mul_f32_e32 v22, v179, v15
	v_mul_f32_e32 v23, v179, v14
	v_fma_f32 v22, v178, v14, -v22
	v_fma_f32 v23, -v178, v15, -v23
	s_nop 1
	v_mfma_f32_16x16x4_f32 v[48:51], v16, v146, v[48:51]
	v_mfma_f32_16x16x4_f32 v[52:55], v18, v146, v[52:55]
	v_mfma_f32_16x16x4_f32 v[56:59], v20, v146, v[56:59]
	v_mfma_f32_16x16x4_f32 v[196:199], v22, v146, v[196:199]
	v_mfma_f32_16x16x4_f32 v[48:51], v17, v147, v[48:51]
	v_mfma_f32_16x16x4_f32 v[52:55], v19, v147, v[52:55]
	v_mfma_f32_16x16x4_f32 v[56:59], v21, v147, v[56:59]
	v_mfma_f32_16x16x4_f32 v[196:199], v23, v147, v[196:199]
	ds_read_b64 v[8:9], v201 offset:4896
	ds_read_b64 v[10:11], v201 offset:4904
	ds_read_b64 v[12:13], v201 offset:4912
	ds_read_b64 v[14:15], v201 offset:4920
	s_waitcnt lgkmcnt(4)
	v_mul_f32_e32 v16, v181, v1
	v_mul_f32_e32 v17, v181, v0
	v_fma_f32 v16, v180, v0, -v16
	v_fma_f32 v17, -v180, v1, -v17
	v_mul_f32_e32 v18, v181, v3
	v_mul_f32_e32 v19, v181, v2
	v_fma_f32 v18, v180, v2, -v18
	v_fma_f32 v19, -v180, v3, -v19
	v_mul_f32_e32 v20, v181, v5
	v_mul_f32_e32 v21, v181, v4
	v_fma_f32 v20, v180, v4, -v20
	v_fma_f32 v21, -v180, v5, -v21
	v_mul_f32_e32 v22, v181, v7
	v_mul_f32_e32 v23, v181, v6
	v_fma_f32 v22, v180, v6, -v22
	v_fma_f32 v23, -v180, v7, -v23
	s_nop 1
	v_mfma_f32_16x16x4_f32 v[48:51], v16, v148, v[48:51]
	v_mfma_f32_16x16x4_f32 v[52:55], v18, v148, v[52:55]
	v_mfma_f32_16x16x4_f32 v[56:59], v20, v148, v[56:59]
	v_mfma_f32_16x16x4_f32 v[196:199], v22, v148, v[196:199]
	v_mfma_f32_16x16x4_f32 v[48:51], v17, v149, v[48:51]
	v_mfma_f32_16x16x4_f32 v[52:55], v19, v149, v[52:55]
	v_mfma_f32_16x16x4_f32 v[56:59], v21, v149, v[56:59]
	v_mfma_f32_16x16x4_f32 v[196:199], v23, v149, v[196:199]
	ds_read_b64 v[0:1], v201 offset:5440
	ds_read_b64 v[2:3], v201 offset:5448
	ds_read_b64 v[4:5], v201 offset:5456
	ds_read_b64 v[6:7], v201 offset:5464
	s_waitcnt lgkmcnt(4)
	v_mul_f32_e32 v16, v183, v9
	v_mul_f32_e32 v17, v183, v8
	v_fma_f32 v16, v182, v8, -v16
	v_fma_f32 v17, -v182, v9, -v17
	v_mul_f32_e32 v18, v183, v11
	v_mul_f32_e32 v19, v183, v10
	v_fma_f32 v18, v182, v10, -v18
	v_fma_f32 v19, -v182, v11, -v19
	v_mul_f32_e32 v20, v183, v13
	v_mul_f32_e32 v21, v183, v12
	v_fma_f32 v20, v182, v12, -v20
	v_fma_f32 v21, -v182, v13, -v21
	v_mul_f32_e32 v22, v183, v15
	v_mul_f32_e32 v23, v183, v14
	v_fma_f32 v22, v182, v14, -v22
	v_fma_f32 v23, -v182, v15, -v23
	s_nop 1
	v_mfma_f32_16x16x4_f32 v[48:51], v16, v150, v[48:51]
	v_mfma_f32_16x16x4_f32 v[52:55], v18, v150, v[52:55]
	v_mfma_f32_16x16x4_f32 v[56:59], v20, v150, v[56:59]
	v_mfma_f32_16x16x4_f32 v[196:199], v22, v150, v[196:199]
	v_mfma_f32_16x16x4_f32 v[48:51], v17, v151, v[48:51]
	v_mfma_f32_16x16x4_f32 v[52:55], v19, v151, v[52:55]
	v_mfma_f32_16x16x4_f32 v[56:59], v21, v151, v[56:59]
	v_mfma_f32_16x16x4_f32 v[196:199], v23, v151, v[196:199]
	ds_read_b64 v[8:9], v201 offset:5984
	ds_read_b64 v[10:11], v201 offset:5992
	ds_read_b64 v[12:13], v201 offset:6000
	ds_read_b64 v[14:15], v201 offset:6008
	s_waitcnt lgkmcnt(4)
	v_mul_f32_e32 v16, v185, v1
	v_mul_f32_e32 v17, v185, v0
	v_fma_f32 v16, v184, v0, -v16
	v_fma_f32 v17, -v184, v1, -v17
	v_mul_f32_e32 v18, v185, v3
	v_mul_f32_e32 v19, v185, v2
	v_fma_f32 v18, v184, v2, -v18
	v_fma_f32 v19, -v184, v3, -v19
	v_mul_f32_e32 v20, v185, v5
	v_mul_f32_e32 v21, v185, v4
	v_fma_f32 v20, v184, v4, -v20
	v_fma_f32 v21, -v184, v5, -v21
	v_mul_f32_e32 v22, v185, v7
	v_mul_f32_e32 v23, v185, v6
	v_fma_f32 v22, v184, v6, -v22
	v_fma_f32 v23, -v184, v7, -v23
	s_nop 1
	v_mfma_f32_16x16x4_f32 v[48:51], v16, v152, v[48:51]
	v_mfma_f32_16x16x4_f32 v[52:55], v18, v152, v[52:55]
	v_mfma_f32_16x16x4_f32 v[56:59], v20, v152, v[56:59]
	v_mfma_f32_16x16x4_f32 v[196:199], v22, v152, v[196:199]
	v_mfma_f32_16x16x4_f32 v[48:51], v17, v153, v[48:51]
	v_mfma_f32_16x16x4_f32 v[52:55], v19, v153, v[52:55]
	v_mfma_f32_16x16x4_f32 v[56:59], v21, v153, v[56:59]
	v_mfma_f32_16x16x4_f32 v[196:199], v23, v153, v[196:199]
	ds_read_b64 v[0:1], v201 offset:6528
	ds_read_b64 v[2:3], v201 offset:6536
	ds_read_b64 v[4:5], v201 offset:6544
	ds_read_b64 v[6:7], v201 offset:6552
	s_waitcnt lgkmcnt(4)
	v_mul_f32_e32 v16, v187, v9
	v_mul_f32_e32 v17, v187, v8
	v_fma_f32 v16, v186, v8, -v16
	v_fma_f32 v17, -v186, v9, -v17
	v_mul_f32_e32 v18, v187, v11
	v_mul_f32_e32 v19, v187, v10
	v_fma_f32 v18, v186, v10, -v18
	v_fma_f32 v19, -v186, v11, -v19
	v_mul_f32_e32 v20, v187, v13
	v_mul_f32_e32 v21, v187, v12
	v_fma_f32 v20, v186, v12, -v20
	v_fma_f32 v21, -v186, v13, -v21
	v_mul_f32_e32 v22, v187, v15
	v_mul_f32_e32 v23, v187, v14
	v_fma_f32 v22, v186, v14, -v22
	v_fma_f32 v23, -v186, v15, -v23
	s_nop 1
	v_mfma_f32_16x16x4_f32 v[48:51], v16, v154, v[48:51]
	v_mfma_f32_16x16x4_f32 v[52:55], v18, v154, v[52:55]
	v_mfma_f32_16x16x4_f32 v[56:59], v20, v154, v[56:59]
	v_mfma_f32_16x16x4_f32 v[196:199], v22, v154, v[196:199]
	v_mfma_f32_16x16x4_f32 v[48:51], v17, v155, v[48:51]
	v_mfma_f32_16x16x4_f32 v[52:55], v19, v155, v[52:55]
	v_mfma_f32_16x16x4_f32 v[56:59], v21, v155, v[56:59]
	v_mfma_f32_16x16x4_f32 v[196:199], v23, v155, v[196:199]
	ds_read_b64 v[8:9], v201 offset:7072
	ds_read_b64 v[10:11], v201 offset:7080
	ds_read_b64 v[12:13], v201 offset:7088
	ds_read_b64 v[14:15], v201 offset:7096
	s_waitcnt lgkmcnt(4)
; __device__ __forceinline__ void s5_gen(LAS unsigned char* lds, const S5In P, int g, int q, bf16_t* Bst, bf16_t* Bout, const int tid) {
;     ...
;       for (int p = 0; p < 64; ++p) { const f32x2v w = pw[(di * 64 + p) * 17 + k]; float zr[4], zi[4];
; #pragma unroll
;           for (int b_ = 0; b_ < 4; ++b_) { const f32x2v b = bb[(di * 64 + p) * 16 + 4 * c2b + b_]; zr[b_] = w.x * b.x - w.y * b.y; zi[b_] = w.x * b.y + w.y * b.x; }
; #pragma unroll
;           for (int a_ = 0; a_ < 4; ++a_) { const f32x2v C = cc[(di * 16 + 4 * chb + a_) * 64 + p];
; #pragma unroll
;               for (int b_ = 0; b_ < 4; ++b_) acc[a_][b_] += C.x * zr[b_] - C.y * zi[b_]; } }
; #pragma unroll
;       for (int a_ = 0; a_ < 4; ++a_)
; #pragma unroll
;           for (int b_ = 0; b_ < 4; ++b_) kt[((di * 16 + k) * 16 + 4 * chb + a_) * 16 + 4 * c2b + b_] = acc[a_][b_]; }
;     __syncthreads();
	v_mul_f32_e32 v16, v189, v1
	v_mul_f32_e32 v17, v189, v0
	v_fma_f32 v16, v188, v0, -v16
	v_fma_f32 v17, -v188, v1, -v17
	v_mul_f32_e32 v18, v189, v3
	v_mul_f32_e32 v19, v189, v2
	v_fma_f32 v18, v188, v2, -v18
	v_fma_f32 v19, -v188, v3, -v19
	v_mul_f32_e32 v20, v189, v5
	v_mul_f32_e32 v21, v189, v4
	v_fma_f32 v20, v188, v4, -v20
	v_fma_f32 v21, -v188, v5, -v21
	v_mul_f32_e32 v22, v189, v7
	v_mul_f32_e32 v23, v189, v6
	v_fma_f32 v22, v188, v6, -v22
	v_fma_f32 v23, -v188, v7, -v23
	s_nop 1
	v_mfma_f32_16x16x4_f32 v[48:51], v16, v156, v[48:51]
	v_mfma_f32_16x16x4_f32 v[52:55], v18, v156, v[52:55]
	v_mfma_f32_16x16x4_f32 v[56:59], v20, v156, v[56:59]
	v_mfma_f32_16x16x4_f32 v[196:199], v22, v156, v[196:199]
	v_mfma_f32_16x16x4_f32 v[48:51], v17, v157, v[48:51]
	v_mfma_f32_16x16x4_f32 v[52:55], v19, v157, v[52:55]
	v_mfma_f32_16x16x4_f32 v[56:59], v21, v157, v[56:59]
	v_mfma_f32_16x16x4_f32 v[196:199], v23, v157, v[196:199]
	ds_read_b64 v[0:1], v201 offset:7616
	ds_read_b64 v[2:3], v201 offset:7624
	ds_read_b64 v[4:5], v201 offset:7632
	ds_read_b64 v[6:7], v201 offset:7640
	s_waitcnt lgkmcnt(4)
	v_mul_f32_e32 v16, v191, v9
	v_mul_f32_e32 v17, v191, v8
	v_fma_f32 v16, v190, v8, -v16
	v_fma_f32 v17, -v190, v9, -v17
	v_mul_f32_e32 v18, v191, v11
	v_mul_f32_e32 v19, v191, v10
	v_fma_f32 v18, v190, v10, -v18
	v_fma_f32 v19, -v190, v11, -v19
	v_mul_f32_e32 v20, v191, v13
	v_mul_f32_e32 v21, v191, v12
	v_fma_f32 v20, v190, v12, -v20
	v_fma_f32 v21, -v190, v13, -v21
	v_mul_f32_e32 v22, v191, v15
	v_mul_f32_e32 v23, v191, v14
	v_fma_f32 v22, v190, v14, -v22
	v_fma_f32 v23, -v190, v15, -v23
	s_nop 1
	v_mfma_f32_16x16x4_f32 v[48:51], v16, v158, v[48:51]
	v_mfma_f32_16x16x4_f32 v[52:55], v18, v158, v[52:55]
	v_mfma_f32_16x16x4_f32 v[56:59], v20, v158, v[56:59]
	v_mfma_f32_16x16x4_f32 v[196:199], v22, v158, v[196:199]
	v_mfma_f32_16x16x4_f32 v[48:51], v17, v159, v[48:51]
	v_mfma_f32_16x16x4_f32 v[52:55], v19, v159, v[52:55]
	v_mfma_f32_16x16x4_f32 v[56:59], v21, v159, v[56:59]
	v_mfma_f32_16x16x4_f32 v[196:199], v23, v159, v[196:199]
	ds_read_b64 v[8:9], v201 offset:8160
	ds_read_b64 v[10:11], v201 offset:8168
	ds_read_b64 v[12:13], v201 offset:8176
	ds_read_b64 v[14:15], v201 offset:8184
	s_waitcnt lgkmcnt(4)
	v_mul_f32_e32 v16, v193, v1
	v_mul_f32_e32 v17, v193, v0
	v_fma_f32 v16, v192, v0, -v16
	v_fma_f32 v17, -v192, v1, -v17
	v_mul_f32_e32 v18, v193, v3
	v_mul_f32_e32 v19, v193, v2
	v_fma_f32 v18, v192, v2, -v18
	v_fma_f32 v19, -v192, v3, -v19
	v_mul_f32_e32 v20, v193, v5
	v_mul_f32_e32 v21, v193, v4
	v_fma_f32 v20, v192, v4, -v20
	v_fma_f32 v21, -v192, v5, -v21
	v_mul_f32_e32 v22, v193, v7
	v_mul_f32_e32 v23, v193, v6
	v_fma_f32 v22, v192, v6, -v22
	v_fma_f32 v23, -v192, v7, -v23
	s_nop 1
	v_mfma_f32_16x16x4_f32 v[48:51], v16, v160, v[48:51]
	v_mfma_f32_16x16x4_f32 v[52:55], v18, v160, v[52:55]
	v_mfma_f32_16x16x4_f32 v[56:59], v20, v160, v[56:59]
	v_mfma_f32_16x16x4_f32 v[196:199], v22, v160, v[196:199]
	v_mfma_f32_16x16x4_f32 v[48:51], v17, v161, v[48:51]
	v_mfma_f32_16x16x4_f32 v[52:55], v19, v161, v[52:55]
	v_mfma_f32_16x16x4_f32 v[56:59], v21, v161, v[56:59]
	v_mfma_f32_16x16x4_f32 v[196:199], v23, v161, v[196:199]
	s_waitcnt lgkmcnt(0)
	v_mul_f32_e32 v16, v195, v9
	v_mul_f32_e32 v17, v195, v8
	v_fma_f32 v16, v194, v8, -v16
	v_fma_f32 v17, -v194, v9, -v17
	v_mul_f32_e32 v18, v195, v11
	v_mul_f32_e32 v19, v195, v10
	v_fma_f32 v18, v194, v10, -v18
	v_fma_f32 v19, -v194, v11, -v19
	v_mul_f32_e32 v20, v195, v13
	v_mul_f32_e32 v21, v195, v12
	v_fma_f32 v20, v194, v12, -v20
	v_fma_f32 v21, -v194, v13, -v21
	v_mul_f32_e32 v22, v195, v15
	v_mul_f32_e32 v23, v195, v14
	v_fma_f32 v22, v194, v14, -v22
	v_fma_f32 v23, -v194, v15, -v23
	s_nop 1
	v_mfma_f32_16x16x4_f32 v[48:51], v16, v162, v[48:51]
	v_mfma_f32_16x16x4_f32 v[52:55], v18, v162, v[52:55]
	v_mfma_f32_16x16x4_f32 v[56:59], v20, v162, v[56:59]
	v_mfma_f32_16x16x4_f32 v[196:199], v22, v162, v[196:199]
	v_mfma_f32_16x16x4_f32 v[48:51], v17, v163, v[48:51]
	v_mfma_f32_16x16x4_f32 v[52:55], v19, v163, v[52:55]
	v_mfma_f32_16x16x4_f32 v[56:59], v21, v163, v[56:59]
	v_mfma_f32_16x16x4_f32 v[196:199], v23, v163, v[196:199]
	s_nop 15
	s_nop 3
	ds_write_b32 v203, v48
	ds_write_b32 v203, v49 offset:64
	ds_write_b32 v203, v50 offset:128
	ds_write_b32 v203, v51 offset:192
	ds_write_b32 v203, v52 offset:1024
	ds_write_b32 v203, v53 offset:1088
	ds_write_b32 v203, v54 offset:1152
	ds_write_b32 v203, v55 offset:1216
	ds_write_b32 v203, v56 offset:2048
	ds_write_b32 v203, v57 offset:2112
	ds_write_b32 v203, v58 offset:2176
	ds_write_b32 v203, v59 offset:2240
	ds_write_b32 v203, v196 offset:3072
	ds_write_b32 v203, v197 offset:3136
	ds_write_b32 v203, v198 offset:3200
	ds_write_b32 v203, v199 offset:3264
	s_and_b32 s48, s53, 3
	s_waitcnt lgkmcnt(0)
	s_barrier
	s_and_saveexec_b64 s[28:29], s[38:39]
	s_movk_i32 s51, 0x5ff
	s_mov_b32 s54, 0xffff0000
	s_cbranch_execz .LBB0_202
; __device__ __forceinline__ unsigned pk2(float lo, float hi) { return f2bf(lo) | (f2bf(hi) << 16); }
; __device__ __forceinline__ void s5_gen(LAS unsigned char* lds, const S5In P, int g, int q, bf16_t* Bst, bf16_t* Bout, const int tid) {
;     ...
;     { const int di = q >> 1, ri = q & 1;
;       for (int cid = tid; cid < 2048; cid += 512) { const int nl = cid >> 5, k0 = (cid & 31) * 8, r = k0 >> 4, ch0 = k0 & 15;
;         const f32x2v w = pw[(di * 64 + nl) * 17 + (di == 0 ? 15 - r : r)]; float v[8];
; #pragma unroll
;         for (int j = 0; j < 8; ++j) { const f32x2v b = bb[(di * 64 + nl) * 16 + ch0 + j]; const float zr = w.x * b.x - w.y * b.y, zi = w.x * b.y + w.y * b.x; v[j] = (ri == 0 ? zr : zi) * P.gain[g * 16 + ch0 + j]; }
;         u32x4 o; o.x = pk2(v[0], v[1]); o.y = pk2(v[2], v[3]); o.z = pk2(v[4], v[5]); o.w = pk2(v[6], v[7]);
;         *(u32x4*)(Bst + ((size_t)g * 256 + q * 64 + nl) * 256 + k0) = o; } }
;     ...
;                 if (r == s && c2 == ch) t += P.dskip[g * 16 + ch];
	v_mbcnt_lo_u32_b32 v43, -1, 0
	v_mbcnt_hi_u32_b32 v43, -1, v43
	v_and_b32_e32 v44, 31, v43
	v_lshrrev_b32_e32 v45, 5, v66
	v_lshrrev_b32_e32 v46, 1, v44
	v_and_b32_e32 v47, 1, v44
	v_lshlrev_b32_e32 v47, 3, v47
	s_lshl_b32 s30, s16, 4
	v_add_u32_e32 v57, s30, v47
	v_lshlrev_b32_e32 v208, 2, v57
	v_lshl_add_u64 v[58:59], s[96:97], 0, v[208:209]
	global_load_dwordx4 v[6:9], v[58:59], off
	global_load_dwordx4 v[10:13], v[58:59], off offset:16
	v_and_b32_e32 v57, 15, v66
	v_add_u32_e32 v57, s30, v57
	v_lshlrev_b32_e32 v208, 2, v57
	v_lshl_add_u64 v[58:59], s[20:21], 0, v[208:209]
	global_load_dword v61, v[58:59], off
	s_lshr_b32 s42, s48, 1
	s_and_b32 s43, s48, 1
	s_cmp_eq_u32 s43, 0
	s_cselect_b64 s[46:47], -1, 0
	s_lshl_b32 s44, s42, 6
	v_add_u32_e32 v57, s44, v45
	v_xor_b32_e32 v58, 15, v46
	s_cmp_eq_u32 s42, 0
	s_cselect_b64 vcc, -1, 0
	v_cndmask_b32_e32 v58, v46, v58, vcc
	v_mul_u32_u24_e32 v52, 0x88, v57
	v_lshl_add_u32 v52, v58, 3, v52
	v_lshlrev_b32_e32 v53, 7, v57
	v_lshl_add_u32 v53, v47, 3, v53
	v_add_u32_e32 v53, 0x4400, v53
	s_lshl_b32 s45, s16, 8
	s_lshl_b32 s17, s48, 6
	s_add_i32 s45, s45, s17
	v_add_u32_e32 v57, s45, v45
	v_lshlrev_b32_e32 v57, 9, v57
	v_lshl_add_u32 v208, v44, 4, v57
	v_lshl_add_u64 v[48:49], s[18:19], 0, v[208:209]
	s_mov_b64 s[50:51], 0x2000
	s_waitcnt vmcnt(0)
	ds_read_b64 v[4:5], v52
	ds_read_b128 v[14:17], v53
	ds_read_b128 v[18:21], v53 offset:16
	ds_read_b128 v[22:25], v53 offset:32
	ds_read_b128 v[26:29], v53 offset:48
	s_waitcnt lgkmcnt(0)
	v_mul_f32_e32 v30, v5, v15
	v_mul_f32_e32 v31, v5, v14
	v_fma_f32 v30, v4, v14, -v30
	v_fma_f32 v31, v4, v15, v31
	v_cndmask_b32_e64 v14, v31, v30, s[46:47]
	v_mul_f32_e32 v14, v14, v6
	v_mul_f32_e32 v30, v5, v17
	v_mul_f32_e32 v31, v5, v16
	v_fma_f32 v30, v4, v16, -v30
	v_fma_f32 v31, v4, v17, v31
	v_cndmask_b32_e64 v16, v31, v30, s[46:47]
	v_mul_f32_e32 v16, v16, v7
	v_mul_f32_e32 v30, v5, v19
	v_mul_f32_e32 v31, v5, v18
	v_fma_f32 v30, v4, v18, -v30
	v_fma_f32 v31, v4, v19, v31
	v_cndmask_b32_e64 v18, v31, v30, s[46:47]
	v_mul_f32_e32 v18, v18, v8
	v_mul_f32_e32 v30, v5, v21
	v_mul_f32_e32 v31, v5, v20
	v_fma_f32 v30, v4, v20, -v30
	v_fma_f32 v31, v4, v21, v31
	v_cndmask_b32_e64 v20, v31, v30, s[46:47]
	v_mul_f32_e32 v20, v20, v9
	v_mul_f32_e32 v30, v5, v23
	v_mul_f32_e32 v31, v5, v22
	v_fma_f32 v30, v4, v22, -v30
	v_fma_f32 v31, v4, v23, v31
	v_cndmask_b32_e64 v22, v31, v30, s[46:47]
	v_mul_f32_e32 v22, v22, v10
	v_mul_f32_e32 v30, v5, v25
	v_mul_f32_e32 v31, v5, v24
	v_fma_f32 v30, v4, v24, -v30
	v_fma_f32 v31, v4, v25, v31
	v_cndmask_b32_e64 v24, v31, v30, s[46:47]
	v_mul_f32_e32 v24, v24, v11
	v_mul_f32_e32 v30, v5, v27
	v_mul_f32_e32 v31, v5, v26
	v_fma_f32 v30, v4, v26, -v30
	v_fma_f32 v31, v4, v27, v31
	v_cndmask_b32_e64 v26, v31, v30, s[46:47]
	v_mul_f32_e32 v26, v26, v12
	v_mul_f32_e32 v30, v5, v29
	v_mul_f32_e32 v31, v5, v28
	v_fma_f32 v30, v4, v28, -v30
	v_fma_f32 v31, v4, v29, v31
	v_cndmask_b32_e64 v28, v31, v30, s[46:47]
	v_mul_f32_e32 v28, v28, v13
	v_cvt_pk_bf16_f32 v0, v14, v16
	v_cvt_pk_bf16_f32 v1, v18, v20
	v_cvt_pk_bf16_f32 v2, v22, v24
	v_cvt_pk_bf16_f32 v3, v26, v28
	global_store_dwordx4 v[48:49], v[0:3], off
	s_nop 1
	v_lshl_add_u64 v[48:49], v[48:49], 0, s[50:51]
	ds_read_b64 v[4:5], v52 offset:2176
	ds_read_b128 v[14:17], v53 offset:2048
	ds_read_b128 v[18:21], v53 offset:2064
	ds_read_b128 v[22:25], v53 offset:2080
	ds_read_b128 v[26:29], v53 offset:2096
	s_waitcnt lgkmcnt(0)
	v_mul_f32_e32 v30, v5, v15
	v_mul_f32_e32 v31, v5, v14
	v_fma_f32 v30, v4, v14, -v30
	v_fma_f32 v31, v4, v15, v31
	v_cndmask_b32_e64 v14, v31, v30, s[46:47]
	v_mul_f32_e32 v14, v14, v6
	v_mul_f32_e32 v30, v5, v17
	v_mul_f32_e32 v31, v5, v16
	v_fma_f32 v30, v4, v16, -v30
	v_fma_f32 v31, v4, v17, v31
	v_cndmask_b32_e64 v16, v31, v30, s[46:47]
	v_mul_f32_e32 v16, v16, v7
	v_mul_f32_e32 v30, v5, v19
	v_mul_f32_e32 v31, v5, v18
	v_fma_f32 v30, v4, v18, -v30
	v_fma_f32 v31, v4, v19, v31
	v_cndmask_b32_e64 v18, v31, v30, s[46:47]
	v_mul_f32_e32 v18, v18, v8
	v_mul_f32_e32 v30, v5, v21
	v_mul_f32_e32 v31, v5, v20
	v_fma_f32 v30, v4, v20, -v30
	v_fma_f32 v31, v4, v21, v31
	v_cndmask_b32_e64 v20, v31, v30, s[46:47]
	v_mul_f32_e32 v20, v20, v9
	v_mul_f32_e32 v30, v5, v23
	v_mul_f32_e32 v31, v5, v22
	v_fma_f32 v30, v4, v22, -v30
	v_fma_f32 v31, v4, v23, v31
	v_cndmask_b32_e64 v22, v31, v30, s[46:47]
	v_mul_f32_e32 v22, v22, v10
	v_mul_f32_e32 v30, v5, v25
	v_mul_f32_e32 v31, v5, v24
	v_fma_f32 v30, v4, v24, -v30
	v_fma_f32 v31, v4, v25, v31
	v_cndmask_b32_e64 v24, v31, v30, s[46:47]
	v_mul_f32_e32 v24, v24, v11
	v_mul_f32_e32 v30, v5, v27
	v_mul_f32_e32 v31, v5, v26
	v_fma_f32 v30, v4, v26, -v30
	v_fma_f32 v31, v4, v27, v31
	v_cndmask_b32_e64 v26, v31, v30, s[46:47]
	v_mul_f32_e32 v26, v26, v12
	v_mul_f32_e32 v30, v5, v29
	v_mul_f32_e32 v31, v5, v28
	v_fma_f32 v30, v4, v28, -v30
	v_fma_f32 v31, v4, v29, v31
	v_cndmask_b32_e64 v28, v31, v30, s[46:47]
	v_mul_f32_e32 v28, v28, v13
	v_cvt_pk_bf16_f32 v0, v14, v16
	v_cvt_pk_bf16_f32 v1, v18, v20
	v_cvt_pk_bf16_f32 v2, v22, v24
	v_cvt_pk_bf16_f32 v3, v26, v28
	global_store_dwordx4 v[48:49], v[0:3], off
	s_nop 1
	v_lshl_add_u64 v[48:49], v[48:49], 0, s[50:51]
	ds_read_b64 v[4:5], v52 offset:4352
	ds_read_b128 v[14:17], v53 offset:4096
	ds_read_b128 v[18:21], v53 offset:4112
	ds_read_b128 v[22:25], v53 offset:4128
	ds_read_b128 v[26:29], v53 offset:4144
	s_waitcnt lgkmcnt(0)
; __device__ __forceinline__ unsigned pk2(float lo, float hi) { return f2bf(lo) | (f2bf(hi) << 16); }
; __device__ __forceinline__ void s5_gen(LAS unsigned char* lds, const S5In P, int g, int q, bf16_t* Bst, bf16_t* Bout, const int tid) {
;     ...
;       for (int cid = tid; cid < 2048; cid += 512) { const int nl = cid >> 5, k0 = (cid & 31) * 8, r = k0 >> 4, ch0 = k0 & 15;
;         const f32x2v w = pw[(di * 64 + nl) * 17 + (di == 0 ? 15 - r : r)]; float v[8];
; #pragma unroll
;         for (int j = 0; j < 8; ++j) { const f32x2v b = bb[(di * 64 + nl) * 16 + ch0 + j]; const float zr = w.x * b.x - w.y * b.y, zi = w.x * b.y + w.y * b.x; v[j] = (ri == 0 ? zr : zi) * P.gain[g * 16 + ch0 + j]; }
;         u32x4 o; o.x = pk2(v[0], v[1]); o.y = pk2(v[2], v[3]); o.z = pk2(v[4], v[5]); o.w = pk2(v[6], v[7]);
;         *(u32x4*)(Bst + ((size_t)g * 256 + q * 64 + nl) * 256 + k0) = o; } }
;     for (int cid = tid; cid < 4096; cid += 512) { const int nl = cid >> 6, k0 = (cid & 63) * 8, n = q * 64 + nl, s = n >> 4, ch = n & 15; float v[8];
;         if (k0 < 256) { const int r = k0 >> 4, c0 = k0 & 15;
; #pragma unroll
;             for (int j = 0; j < 8; ++j) { const int c2 = c0 + j; float t = 0.f;
;                 if (r <= s) t += kt[((0 * 16 + (s - r)) * 16 + ch) * 16 + c2];
;                 if (r >= s) t += kt[((1 * 16 + (r - s)) * 16 + ch) * 16 + c2];
;                 if (r == s && c2 == ch) t += P.dskip[g * 16 + ch];
;                 v[j] = t * P.gain[g * 16 + c2]; }
;         } else { const int kk = k0 - 256, di = kk >> 7, ri = (kk >> 6) & 1, p0 = kk & 63;
	v_mul_f32_e32 v30, v5, v15
	v_mul_f32_e32 v31, v5, v14
	v_fma_f32 v30, v4, v14, -v30
	v_fma_f32 v31, v4, v15, v31
	v_cndmask_b32_e64 v14, v31, v30, s[46:47]
	v_mul_f32_e32 v14, v14, v6
	v_mul_f32_e32 v30, v5, v17
	v_mul_f32_e32 v31, v5, v16
	v_fma_f32 v30, v4, v16, -v30
	v_fma_f32 v31, v4, v17, v31
	v_cndmask_b32_e64 v16, v31, v30, s[46:47]
	v_mul_f32_e32 v16, v16, v7
	v_mul_f32_e32 v30, v5, v19
	v_mul_f32_e32 v31, v5, v18
	v_fma_f32 v30, v4, v18, -v30
	v_fma_f32 v31, v4, v19, v31
	v_cndmask_b32_e64 v18, v31, v30, s[46:47]
	v_mul_f32_e32 v18, v18, v8
	v_mul_f32_e32 v30, v5, v21
	v_mul_f32_e32 v31, v5, v20
	v_fma_f32 v30, v4, v20, -v30
	v_fma_f32 v31, v4, v21, v31
	v_cndmask_b32_e64 v20, v31, v30, s[46:47]
	v_mul_f32_e32 v20, v20, v9
	v_mul_f32_e32 v30, v5, v23
	v_mul_f32_e32 v31, v5, v22
	v_fma_f32 v30, v4, v22, -v30
	v_fma_f32 v31, v4, v23, v31
	v_cndmask_b32_e64 v22, v31, v30, s[46:47]
	v_mul_f32_e32 v22, v22, v10
	v_mul_f32_e32 v30, v5, v25
	v_mul_f32_e32 v31, v5, v24
	v_fma_f32 v30, v4, v24, -v30
	v_fma_f32 v31, v4, v25, v31
	v_cndmask_b32_e64 v24, v31, v30, s[46:47]
	v_mul_f32_e32 v24, v24, v11
	v_mul_f32_e32 v30, v5, v27
	v_mul_f32_e32 v31, v5, v26
	v_fma_f32 v30, v4, v26, -v30
	v_fma_f32 v31, v4, v27, v31
	v_cndmask_b32_e64 v26, v31, v30, s[46:47]
	v_mul_f32_e32 v26, v26, v12
	v_mul_f32_e32 v30, v5, v29
	v_mul_f32_e32 v31, v5, v28
	v_fma_f32 v30, v4, v28, -v30
	v_fma_f32 v31, v4, v29, v31
	v_cndmask_b32_e64 v28, v31, v30, s[46:47]
	v_mul_f32_e32 v28, v28, v13
	v_cvt_pk_bf16_f32 v0, v14, v16
	v_cvt_pk_bf16_f32 v1, v18, v20
	v_cvt_pk_bf16_f32 v2, v22, v24
	v_cvt_pk_bf16_f32 v3, v26, v28
	global_store_dwordx4 v[48:49], v[0:3], off
	s_nop 1
	v_lshl_add_u64 v[48:49], v[48:49], 0, s[50:51]
	ds_read_b64 v[4:5], v52 offset:6528
	ds_read_b128 v[14:17], v53 offset:6144
	ds_read_b128 v[18:21], v53 offset:6160
	ds_read_b128 v[22:25], v53 offset:6176
	ds_read_b128 v[26:29], v53 offset:6192
	s_waitcnt lgkmcnt(0)
	v_mul_f32_e32 v30, v5, v15
	v_mul_f32_e32 v31, v5, v14
	v_fma_f32 v30, v4, v14, -v30
	v_fma_f32 v31, v4, v15, v31
	v_cndmask_b32_e64 v14, v31, v30, s[46:47]
	v_mul_f32_e32 v14, v14, v6
	v_mul_f32_e32 v30, v5, v17
	v_mul_f32_e32 v31, v5, v16
	v_fma_f32 v30, v4, v16, -v30
	v_fma_f32 v31, v4, v17, v31
	v_cndmask_b32_e64 v16, v31, v30, s[46:47]
	v_mul_f32_e32 v16, v16, v7
	v_mul_f32_e32 v30, v5, v19
	v_mul_f32_e32 v31, v5, v18
	v_fma_f32 v30, v4, v18, -v30
	v_fma_f32 v31, v4, v19, v31
	v_cndmask_b32_e64 v18, v31, v30, s[46:47]
	v_mul_f32_e32 v18, v18, v8
	v_mul_f32_e32 v30, v5, v21
	v_mul_f32_e32 v31, v5, v20
	v_fma_f32 v30, v4, v20, -v30
	v_fma_f32 v31, v4, v21, v31
	v_cndmask_b32_e64 v20, v31, v30, s[46:47]
	v_mul_f32_e32 v20, v20, v9
	v_mul_f32_e32 v30, v5, v23
	v_mul_f32_e32 v31, v5, v22
	v_fma_f32 v30, v4, v22, -v30
	v_fma_f32 v31, v4, v23, v31
	v_cndmask_b32_e64 v22, v31, v30, s[46:47]
	v_mul_f32_e32 v22, v22, v10
	v_mul_f32_e32 v30, v5, v25
	v_mul_f32_e32 v31, v5, v24
	v_fma_f32 v30, v4, v24, -v30
	v_fma_f32 v31, v4, v25, v31
	v_cndmask_b32_e64 v24, v31, v30, s[46:47]
	v_mul_f32_e32 v24, v24, v11
	v_mul_f32_e32 v30, v5, v27
	v_mul_f32_e32 v31, v5, v26
	v_fma_f32 v30, v4, v26, -v30
	v_fma_f32 v31, v4, v27, v31
	v_cndmask_b32_e64 v26, v31, v30, s[46:47]
	v_mul_f32_e32 v26, v26, v12
	v_mul_f32_e32 v30, v5, v29
	v_mul_f32_e32 v31, v5, v28
	v_fma_f32 v30, v4, v28, -v30
	v_fma_f32 v31, v4, v29, v31
	v_cndmask_b32_e64 v28, v31, v30, s[46:47]
	v_mul_f32_e32 v28, v28, v13
	v_cvt_pk_bf16_f32 v0, v14, v16
	v_cvt_pk_bf16_f32 v1, v18, v20
	v_cvt_pk_bf16_f32 v2, v22, v24
	v_cvt_pk_bf16_f32 v3, v26, v28
	global_store_dwordx4 v[48:49], v[0:3], off
	s_nop 1
.LBB0_202:
	s_or_b64 exec, exec, s[28:29]
	s_and_saveexec_b64 s[28:29], s[40:41]
	s_cbranch_execz .LBB0_191
	s_ashr_i32 s17, s16, 31
	s_lshl_b32 s54, s48, 6
	s_lshl_b32 s30, s16, 4
	s_lshl_b64 s[16:17], s[16:17], 18
	s_add_u32 s16, s5, s16
	s_addc_u32 s17, s52, s17
	v_mbcnt_lo_u32_b32 v43, -1, 0
	v_mbcnt_hi_u32_b32 v43, -1, v43
	v_lshrrev_b32_e32 v44, 6, v66
	s_nop 0
	v_readfirstlane_b32 s42, v44
	v_lshrrev_b32_e32 v44, 5, v43
	v_and_b32_e32 v45, 31, v43
	v_and_b32_e32 v47, 1, v43
	v_lshlrev_b32_e32 v47, 3, v47
	v_and_b32_e32 v57, 15, v66
	v_lshrrev_b32_e32 v60, 4, v66
	s_lshr_b32 s43, s54, 4
	s_lshr_b32 s44, s42, 1
	s_add_i32 s43, s43, s44
	s_and_b32 s44, s42, 1
	s_lshl_b32 s44, s44, 3
	s_lshl_b32 s45, s42, 3
	s_add_i32 s45, s45, s54
	s_mov_b64 s[50:51], 0x800
	v_add_u32_e32 v46, s44, v44
	v_cmp_eq_u32_e32 vcc, v57, v60
	v_lshlrev_b32_e32 v60, 2, v66
	v_add_u32_e32 v60, 0x14400, v60
	v_cndmask_b32_e32 v61, 0, v61, vcc
	ds_write_b32 v60, v61
	v_lshrrev_b32_e32 v57, 1, v45
	v_sub_u32_e32 v58, s43, v57
	v_subrev_u32_e32 v59, s43, v57
	v_lshlrev_b32_e32 v60, 6, v46
	v_lshl_add_u32 v60, v47, 2, v60
	v_lshl_add_u32 v52, v58, 10, v60
	v_add_u32_e32 v52, 0xc400, v52
	v_lshl_add_u32 v53, v59, 10, v60
	v_add_u32_e32 v53, 0x10400, v53
	v_add_u32_e32 v54, 0x14400, v60
	v_mov_b32_e32 v61, 0x14800
	v_cmp_le_i32_e32 vcc, 0, v58
	v_cndmask_b32_e32 v52, v61, v52, vcc
	v_cmp_le_i32_e32 vcc, 0, v59
	v_cndmask_b32_e32 v53, v61, v53, vcc
	v_cmp_eq_u32_e32 vcc, s43, v57
	v_cndmask_b32_e32 v54, v61, v54, vcc
	v_add_u32_e32 v57, s45, v44
	v_lshlrev_b32_e32 v57, 10, v57
	v_lshl_add_u32 v208, v45, 4, v57
	v_lshl_add_u64 v[48:49], s[16:17], 0, v[208:209]
	v_add_u32_e32 v208, 0x200, v208
	v_lshl_add_u64 v[50:51], s[16:17], 0, v[208:209]
	v_lshrrev_b32_e32 v57, 4, v45
	v_and_b32_e32 v58, 7, v45
	v_lshlrev_b32_e32 v58, 3, v58
	v_lshlrev_b32_e32 v55, 13, v57
	v_lshl_add_u32 v55, v46, 9, v55
	v_lshl_add_u32 v55, v58, 3, v55
	v_add_u32_e32 v55, 0x8400, v55
	s_add_i32 s46, s43, 1
	s_sub_i32 s47, 16, s43
	v_mov_b32_e32 v59, s47
	v_mov_b32_e32 v60, s46
	v_cmp_eq_u32_e32 vcc, 0, v57
	v_cndmask_b32_e32 v59, v59, v60, vcc
	v_lshl_add_u32 v56, v57, 6, v58
	v_mul_u32_u24_e32 v56, 0x88, v56
	v_lshl_add_u32 v56, v59, 3, v56
	v_and_b32_e32 v57, 8, v45
	v_cmp_eq_u32_e64 s[46:47], 0, v57
	s_waitcnt lgkmcnt(0)
	s_barrier
; __device__ __forceinline__ void s5_gen(LAS unsigned char* lds, const S5In P, int g, int q, bf16_t* Bst, bf16_t* Bout, const int tid) {
;     ...
;     for (int cid = tid; cid < 4096; cid += 512) { const int nl = cid >> 6, k0 = (cid & 63) * 8, n = q * 64 + nl, s = n >> 4, ch = n & 15; float v[8];
;         if (k0 < 256) { const int r = k0 >> 4, c0 = k0 & 15;
; #pragma unroll
;             for (int j = 0; j < 8; ++j) { const int c2 = c0 + j; float t = 0.f;
;                 if (r <= s) t += kt[((0 * 16 + (s - r)) * 16 + ch) * 16 + c2];
;                 if (r >= s) t += kt[((1 * 16 + (r - s)) * 16 + ch) * 16 + c2];
;                 if (r == s && c2 == ch) t += P.dskip[g * 16 + ch];
;                 v[j] = t * P.gain[g * 16 + c2]; }
;         } else { const int kk = k0 - 256, di = kk >> 7, ri = (kk >> 6) & 1, p0 = kk & 63;
; #pragma unroll
;             for (int j = 0; j < 8; ++j) { const int p = p0 + j; const f32x2v C = cc[(di * 16 + ch) * 64 + p], w = pw[(di * 64 + p) * 17 + (di == 0 ? s + 1 : 16 - s)];
;                 v[j] = ri == 0 ? (C.x * w.x - C.y * w.y) : -(C.x * w.y + C.y * w.x); } }
	ds_read_b128 v[14:17], v52 offset:0
	ds_read_b128 v[18:21], v52 offset:16
	ds_read_b128 v[22:25], v53 offset:0
	ds_read_b128 v[26:29], v53 offset:16
	ds_read_b128 v[30:33], v54 offset:0
	ds_read_b128 v[0:3], v54 offset:16
	s_waitcnt lgkmcnt(2)
	v_pk_add_f32 v[14:15], v[14:15], v[22:23]
	v_pk_add_f32 v[16:17], v[16:17], v[24:25]
	v_pk_add_f32 v[18:19], v[18:19], v[26:27]
	v_pk_add_f32 v[20:21], v[20:21], v[28:29]
	s_waitcnt lgkmcnt(0)
	v_pk_add_f32 v[14:15], v[14:15], v[30:31]
	v_pk_add_f32 v[16:17], v[16:17], v[32:33]
	v_pk_add_f32 v[18:19], v[18:19], v[0:1]
	v_pk_add_f32 v[20:21], v[20:21], v[2:3]
	v_pk_mul_f32 v[14:15], v[14:15], v[6:7]
	v_pk_mul_f32 v[16:17], v[16:17], v[8:9]
	v_pk_mul_f32 v[18:19], v[18:19], v[10:11]
	v_pk_mul_f32 v[20:21], v[20:21], v[12:13]
	v_cvt_pk_bf16_f32 v22, v14, v15
	v_cvt_pk_bf16_f32 v23, v16, v17
	v_cvt_pk_bf16_f32 v24, v18, v19
	v_cvt_pk_bf16_f32 v25, v20, v21
	global_store_dwordx4 v[48:49], v[22:25], off
	s_nop 1
	v_lshl_add_u64 v[48:49], v[48:49], 0, s[50:51]
	ds_read_b128 v[14:17], v52 offset:128
	ds_read_b128 v[18:21], v52 offset:144
	ds_read_b128 v[22:25], v53 offset:128
	ds_read_b128 v[26:29], v53 offset:144
	ds_read_b128 v[30:33], v54 offset:128
	ds_read_b128 v[0:3], v54 offset:144
	s_waitcnt lgkmcnt(2)
	v_pk_add_f32 v[14:15], v[14:15], v[22:23]
	v_pk_add_f32 v[16:17], v[16:17], v[24:25]
	v_pk_add_f32 v[18:19], v[18:19], v[26:27]
	v_pk_add_f32 v[20:21], v[20:21], v[28:29]
	s_waitcnt lgkmcnt(0)
	v_pk_add_f32 v[14:15], v[14:15], v[30:31]
	v_pk_add_f32 v[16:17], v[16:17], v[32:33]
	v_pk_add_f32 v[18:19], v[18:19], v[0:1]
	v_pk_add_f32 v[20:21], v[20:21], v[2:3]
	v_pk_mul_f32 v[14:15], v[14:15], v[6:7]
	v_pk_mul_f32 v[16:17], v[16:17], v[8:9]
	v_pk_mul_f32 v[18:19], v[18:19], v[10:11]
	v_pk_mul_f32 v[20:21], v[20:21], v[12:13]
	v_cvt_pk_bf16_f32 v22, v14, v15
	v_cvt_pk_bf16_f32 v23, v16, v17
	v_cvt_pk_bf16_f32 v24, v18, v19
	v_cvt_pk_bf16_f32 v25, v20, v21
	global_store_dwordx4 v[48:49], v[22:25], off
	s_nop 1
	v_lshl_add_u64 v[48:49], v[48:49], 0, s[50:51]
	ds_read_b128 v[14:17], v52 offset:256
	ds_read_b128 v[18:21], v52 offset:272
	ds_read_b128 v[22:25], v53 offset:256
	ds_read_b128 v[26:29], v53 offset:272
	ds_read_b128 v[30:33], v54 offset:256
	ds_read_b128 v[0:3], v54 offset:272
	s_waitcnt lgkmcnt(2)
	v_pk_add_f32 v[14:15], v[14:15], v[22:23]
	v_pk_add_f32 v[16:17], v[16:17], v[24:25]
	v_pk_add_f32 v[18:19], v[18:19], v[26:27]
	v_pk_add_f32 v[20:21], v[20:21], v[28:29]
	s_waitcnt lgkmcnt(0)
	v_pk_add_f32 v[14:15], v[14:15], v[30:31]
	v_pk_add_f32 v[16:17], v[16:17], v[32:33]
	v_pk_add_f32 v[18:19], v[18:19], v[0:1]
	v_pk_add_f32 v[20:21], v[20:21], v[2:3]
	v_pk_mul_f32 v[14:15], v[14:15], v[6:7]
	v_pk_mul_f32 v[16:17], v[16:17], v[8:9]
	v_pk_mul_f32 v[18:19], v[18:19], v[10:11]
	v_pk_mul_f32 v[20:21], v[20:21], v[12:13]
	v_cvt_pk_bf16_f32 v22, v14, v15
	v_cvt_pk_bf16_f32 v23, v16, v17
	v_cvt_pk_bf16_f32 v24, v18, v19
	v_cvt_pk_bf16_f32 v25, v20, v21
	global_store_dwordx4 v[48:49], v[22:25], off
	s_nop 1
	v_lshl_add_u64 v[48:49], v[48:49], 0, s[50:51]
	ds_read_b128 v[14:17], v52 offset:384
	ds_read_b128 v[18:21], v52 offset:400
	ds_read_b128 v[22:25], v53 offset:384
	ds_read_b128 v[26:29], v53 offset:400
	ds_read_b128 v[30:33], v54 offset:384
	ds_read_b128 v[0:3], v54 offset:400
	s_waitcnt lgkmcnt(2)
	v_pk_add_f32 v[14:15], v[14:15], v[22:23]
	v_pk_add_f32 v[16:17], v[16:17], v[24:25]
	v_pk_add_f32 v[18:19], v[18:19], v[26:27]
	v_pk_add_f32 v[20:21], v[20:21], v[28:29]
	s_waitcnt lgkmcnt(0)
	v_pk_add_f32 v[14:15], v[14:15], v[30:31]
	v_pk_add_f32 v[16:17], v[16:17], v[32:33]
	v_pk_add_f32 v[18:19], v[18:19], v[0:1]
	v_pk_add_f32 v[20:21], v[20:21], v[2:3]
	v_pk_mul_f32 v[14:15], v[14:15], v[6:7]
	v_pk_mul_f32 v[16:17], v[16:17], v[8:9]
	v_pk_mul_f32 v[18:19], v[18:19], v[10:11]
	v_pk_mul_f32 v[20:21], v[20:21], v[12:13]
	v_cvt_pk_bf16_f32 v22, v14, v15
	v_cvt_pk_bf16_f32 v23, v16, v17
	v_cvt_pk_bf16_f32 v24, v18, v19
	v_cvt_pk_bf16_f32 v25, v20, v21
	global_store_dwordx4 v[48:49], v[22:25], off
	s_nop 1
	ds_read_b64 v[6:7], v56
	ds_read_b64 v[8:9], v56 offset:136
	ds_read_b64 v[10:11], v56 offset:272
	ds_read_b64 v[12:13], v56 offset:408
	ds_read_b64 v[14:15], v56 offset:544
	ds_read_b64 v[16:17], v56 offset:680
	ds_read_b64 v[18:19], v56 offset:816
	ds_read_b64 v[20:21], v56 offset:952
	ds_read_b128 v[22:25], v55 offset:0
	ds_read_b128 v[26:29], v55 offset:16
	ds_read_b128 v[30:33], v55 offset:32
	ds_read_b128 v[0:3], v55 offset:48
	s_waitcnt lgkmcnt(0)
	v_mul_f32_e32 v4, v23, v7
	v_mul_f32_e32 v5, v23, v6
	v_fma_f32 v4, v22, v6, -v4
	v_fma_f32 v5, v22, v7, v5
	v_cndmask_b32_e64 v22, -v5, v4, s[46:47]
	v_mul_f32_e32 v4, v25, v9
	v_mul_f32_e32 v5, v25, v8
	v_fma_f32 v4, v24, v8, -v4
	v_fma_f32 v5, v24, v9, v5
	v_cndmask_b32_e64 v24, -v5, v4, s[46:47]
	v_mul_f32_e32 v4, v27, v11
	v_mul_f32_e32 v5, v27, v10
	v_fma_f32 v4, v26, v10, -v4
	v_fma_f32 v5, v26, v11, v5
	v_cndmask_b32_e64 v26, -v5, v4, s[46:47]
	v_mul_f32_e32 v4, v29, v13
	v_mul_f32_e32 v5, v29, v12
	v_fma_f32 v4, v28, v12, -v4
	v_fma_f32 v5, v28, v13, v5
	v_cndmask_b32_e64 v28, -v5, v4, s[46:47]
	v_mul_f32_e32 v4, v31, v15
	v_mul_f32_e32 v5, v31, v14
	v_fma_f32 v4, v30, v14, -v4
	v_fma_f32 v5, v30, v15, v5
	v_cndmask_b32_e64 v30, -v5, v4, s[46:47]
	v_mul_f32_e32 v4, v33, v17
	v_mul_f32_e32 v5, v33, v16
	v_fma_f32 v4, v32, v16, -v4
	v_fma_f32 v5, v32, v17, v5
	v_cndmask_b32_e64 v32, -v5, v4, s[46:47]
	v_mul_f32_e32 v4, v1, v19
	v_mul_f32_e32 v5, v1, v18
	v_fma_f32 v4, v0, v18, -v4
	v_fma_f32 v5, v0, v19, v5
	v_cndmask_b32_e64 v0, -v5, v4, s[46:47]
	v_mul_f32_e32 v4, v3, v21
	v_mul_f32_e32 v5, v3, v20
	v_fma_f32 v4, v2, v20, -v4
	v_fma_f32 v5, v2, v21, v5
	v_cndmask_b32_e64 v2, -v5, v4, s[46:47]
	v_cvt_pk_bf16_f32 v58, v22, v24
	v_cvt_pk_bf16_f32 v59, v26, v28
	v_cvt_pk_bf16_f32 v60, v30, v32
	v_cvt_pk_bf16_f32 v61, v0, v2
	global_store_dwordx4 v[50:51], v[58:61], off
	s_nop 1
	v_lshl_add_u64 v[50:51], v[50:51], 0, s[50:51]
	ds_read_b128 v[22:25], v55 offset:1024
	ds_read_b128 v[26:29], v55 offset:1040
	ds_read_b128 v[30:33], v55 offset:1056
	ds_read_b128 v[0:3], v55 offset:1072
	s_waitcnt lgkmcnt(0)
; __device__ __forceinline__ unsigned pk2(float lo, float hi) { return f2bf(lo) | (f2bf(hi) << 16); }
; __device__ __forceinline__ void s5_gen(LAS unsigned char* lds, const S5In P, int g, int q, bf16_t* Bst, bf16_t* Bout, const int tid) {
;     ...
;         } else { const int kk = k0 - 256, di = kk >> 7, ri = (kk >> 6) & 1, p0 = kk & 63;
; #pragma unroll
;             for (int j = 0; j < 8; ++j) { const int p = p0 + j; const f32x2v C = cc[(di * 16 + ch) * 64 + p], w = pw[(di * 64 + p) * 17 + (di == 0 ? s + 1 : 16 - s)];
;                 v[j] = ri == 0 ? (C.x * w.x - C.y * w.y) : -(C.x * w.y + C.y * w.x); } }
;         u32x4 o; o.x = pk2(v[0], v[1]); o.y = pk2(v[2], v[3]); o.z = pk2(v[4], v[5]); o.w = pk2(v[6], v[7]);
;         *(u32x4*)(Bout + ((size_t)g * 256 + n) * 512 + k0) = o; }
;     __syncthreads();
	v_mul_f32_e32 v4, v23, v7
	v_mul_f32_e32 v5, v23, v6
	v_fma_f32 v4, v22, v6, -v4
	v_fma_f32 v5, v22, v7, v5
	v_cndmask_b32_e64 v22, -v5, v4, s[46:47]
	v_mul_f32_e32 v4, v25, v9
	v_mul_f32_e32 v5, v25, v8
	v_fma_f32 v4, v24, v8, -v4
	v_fma_f32 v5, v24, v9, v5
	v_cndmask_b32_e64 v24, -v5, v4, s[46:47]
	v_mul_f32_e32 v4, v27, v11
	v_mul_f32_e32 v5, v27, v10
	v_fma_f32 v4, v26, v10, -v4
	v_fma_f32 v5, v26, v11, v5
	v_cndmask_b32_e64 v26, -v5, v4, s[46:47]
	v_mul_f32_e32 v4, v29, v13
	v_mul_f32_e32 v5, v29, v12
	v_fma_f32 v4, v28, v12, -v4
	v_fma_f32 v5, v28, v13, v5
	v_cndmask_b32_e64 v28, -v5, v4, s[46:47]
	v_mul_f32_e32 v4, v31, v15
	v_mul_f32_e32 v5, v31, v14
	v_fma_f32 v4, v30, v14, -v4
	v_fma_f32 v5, v30, v15, v5
	v_cndmask_b32_e64 v30, -v5, v4, s[46:47]
	v_mul_f32_e32 v4, v33, v17
	v_mul_f32_e32 v5, v33, v16
	v_fma_f32 v4, v32, v16, -v4
	v_fma_f32 v5, v32, v17, v5
	v_cndmask_b32_e64 v32, -v5, v4, s[46:47]
	v_mul_f32_e32 v4, v1, v19
	v_mul_f32_e32 v5, v1, v18
	v_fma_f32 v4, v0, v18, -v4
	v_fma_f32 v5, v0, v19, v5
	v_cndmask_b32_e64 v0, -v5, v4, s[46:47]
	v_mul_f32_e32 v4, v3, v21
	v_mul_f32_e32 v5, v3, v20
	v_fma_f32 v4, v2, v20, -v4
	v_fma_f32 v5, v2, v21, v5
	v_cndmask_b32_e64 v2, -v5, v4, s[46:47]
	v_cvt_pk_bf16_f32 v58, v22, v24
	v_cvt_pk_bf16_f32 v59, v26, v28
	v_cvt_pk_bf16_f32 v60, v30, v32
	v_cvt_pk_bf16_f32 v61, v0, v2
	global_store_dwordx4 v[50:51], v[58:61], off
	s_nop 1
	v_lshl_add_u64 v[50:51], v[50:51], 0, s[50:51]
	ds_read_b128 v[22:25], v55 offset:2048
	ds_read_b128 v[26:29], v55 offset:2064
	ds_read_b128 v[30:33], v55 offset:2080
	ds_read_b128 v[0:3], v55 offset:2096
	s_waitcnt lgkmcnt(0)
	v_mul_f32_e32 v4, v23, v7
	v_mul_f32_e32 v5, v23, v6
	v_fma_f32 v4, v22, v6, -v4
	v_fma_f32 v5, v22, v7, v5
	v_cndmask_b32_e64 v22, -v5, v4, s[46:47]
	v_mul_f32_e32 v4, v25, v9
	v_mul_f32_e32 v5, v25, v8
	v_fma_f32 v4, v24, v8, -v4
	v_fma_f32 v5, v24, v9, v5
	v_cndmask_b32_e64 v24, -v5, v4, s[46:47]
	v_mul_f32_e32 v4, v27, v11
	v_mul_f32_e32 v5, v27, v10
	v_fma_f32 v4, v26, v10, -v4
	v_fma_f32 v5, v26, v11, v5
	v_cndmask_b32_e64 v26, -v5, v4, s[46:47]
	v_mul_f32_e32 v4, v29, v13
	v_mul_f32_e32 v5, v29, v12
	v_fma_f32 v4, v28, v12, -v4
	v_fma_f32 v5, v28, v13, v5
	v_cndmask_b32_e64 v28, -v5, v4, s[46:47]
	v_mul_f32_e32 v4, v31, v15
	v_mul_f32_e32 v5, v31, v14
	v_fma_f32 v4, v30, v14, -v4
	v_fma_f32 v5, v30, v15, v5
	v_cndmask_b32_e64 v30, -v5, v4, s[46:47]
	v_mul_f32_e32 v4, v33, v17
	v_mul_f32_e32 v5, v33, v16
	v_fma_f32 v4, v32, v16, -v4
	v_fma_f32 v5, v32, v17, v5
	v_cndmask_b32_e64 v32, -v5, v4, s[46:47]
	v_mul_f32_e32 v4, v1, v19
	v_mul_f32_e32 v5, v1, v18
	v_fma_f32 v4, v0, v18, -v4
	v_fma_f32 v5, v0, v19, v5
	v_cndmask_b32_e64 v0, -v5, v4, s[46:47]
	v_mul_f32_e32 v4, v3, v21
	v_mul_f32_e32 v5, v3, v20
	v_fma_f32 v4, v2, v20, -v4
	v_fma_f32 v5, v2, v21, v5
	v_cndmask_b32_e64 v2, -v5, v4, s[46:47]
	v_cvt_pk_bf16_f32 v58, v22, v24
	v_cvt_pk_bf16_f32 v59, v26, v28
	v_cvt_pk_bf16_f32 v60, v30, v32
	v_cvt_pk_bf16_f32 v61, v0, v2
	global_store_dwordx4 v[50:51], v[58:61], off
	s_nop 1
	v_lshl_add_u64 v[50:51], v[50:51], 0, s[50:51]
	ds_read_b128 v[22:25], v55 offset:3072
	ds_read_b128 v[26:29], v55 offset:3088
	ds_read_b128 v[30:33], v55 offset:3104
	ds_read_b128 v[0:3], v55 offset:3120
	s_waitcnt lgkmcnt(0)
	v_mul_f32_e32 v4, v23, v7
	v_mul_f32_e32 v5, v23, v6
	v_fma_f32 v4, v22, v6, -v4
	v_fma_f32 v5, v22, v7, v5
	v_cndmask_b32_e64 v22, -v5, v4, s[46:47]
	v_mul_f32_e32 v4, v25, v9
	v_mul_f32_e32 v5, v25, v8
	v_fma_f32 v4, v24, v8, -v4
	v_fma_f32 v5, v24, v9, v5
	v_cndmask_b32_e64 v24, -v5, v4, s[46:47]
	v_mul_f32_e32 v4, v27, v11
	v_mul_f32_e32 v5, v27, v10
	v_fma_f32 v4, v26, v10, -v4
	v_fma_f32 v5, v26, v11, v5
	v_cndmask_b32_e64 v26, -v5, v4, s[46:47]
	v_mul_f32_e32 v4, v29, v13
	v_mul_f32_e32 v5, v29, v12
	v_fma_f32 v4, v28, v12, -v4
	v_fma_f32 v5, v28, v13, v5
	v_cndmask_b32_e64 v28, -v5, v4, s[46:47]
	v_mul_f32_e32 v4, v31, v15
	v_mul_f32_e32 v5, v31, v14
	v_fma_f32 v4, v30, v14, -v4
	v_fma_f32 v5, v30, v15, v5
	v_cndmask_b32_e64 v30, -v5, v4, s[46:47]
	v_mul_f32_e32 v4, v33, v17
	v_mul_f32_e32 v5, v33, v16
	v_fma_f32 v4, v32, v16, -v4
	v_fma_f32 v5, v32, v17, v5
	v_cndmask_b32_e64 v32, -v5, v4, s[46:47]
	v_mul_f32_e32 v4, v1, v19
	v_mul_f32_e32 v5, v1, v18
	v_fma_f32 v4, v0, v18, -v4
	v_fma_f32 v5, v0, v19, v5
	v_cndmask_b32_e64 v0, -v5, v4, s[46:47]
	v_mul_f32_e32 v4, v3, v21
	v_mul_f32_e32 v5, v3, v20
	v_fma_f32 v4, v2, v20, -v4
	v_fma_f32 v5, v2, v21, v5
	v_cndmask_b32_e64 v2, -v5, v4, s[46:47]
	v_cvt_pk_bf16_f32 v58, v22, v24
	v_cvt_pk_bf16_f32 v59, v26, v28
	v_cvt_pk_bf16_f32 v60, v30, v32
	v_cvt_pk_bf16_f32 v61, v0, v2
	global_store_dwordx4 v[50:51], v[58:61], off
	s_nop 1
	s_branch .LBB0_191

; __device__ __forceinline__ unsigned cvt_pk_bf16(float lo, float hi) { unsigned r; asm volatile("v_cvt_pk_bf16_f32 %0, %1, %2" : "=v"(r) : "v"(lo), "v"(hi)); return r; }
; #define LAS __attribute__((address_space(3)))
; template <bool F32SRC> __device__ __forceinline__ void unorm_chunk(LAS unsigned char* lds, const float* xsrc, bf16_t* hbio, bf16_t* Ug, int chunk, const int tid) {
;     ...
;         } else { const u32x4* xr = (const u32x4*)(hbio + row * DM) + lane; u32x4 w[2]; float v[16]; float ss = 0.f;
; #pragma unroll
;             for (int j = 0; j < 2; ++j) { w[j] = xr[64 * j];
;                 v[8 * j + 0] = __uint_as_float(w[j].x << 16); v[8 * j + 1] = __uint_as_float(w[j].x & 0xffff0000u); v[8 * j + 2] = __uint_as_float(w[j].y << 16); v[8 * j + 3] = __uint_as_float(w[j].y & 0xffff0000u);
;                 v[8 * j + 4] = __uint_as_float(w[j].z << 16); v[8 * j + 5] = __uint_as_float(w[j].z & 0xffff0000u); v[8 * j + 6] = __uint_as_float(w[j].w << 16); v[8 * j + 7] = __uint_as_float(w[j].w & 0xffff0000u); }
; #pragma unroll
;             for (int i = 0; i < 16; ++i) ss += v[i] * v[i];
;             const float rstd = rsqrtf(wsum_l(ss, lane) * (1.0f / DM) + EPS);
; #pragma unroll
;             for (int j = 0; j < 2; ++j) { u32x4 q; q.x = pg8::cvt_pk_bf16(v[8 * j] * rstd, v[8 * j + 1] * rstd); q.y = pg8::cvt_pk_bf16(v[8 * j + 2] * rstd, v[8 * j + 3] * rstd);
;                 q.z = pg8::cvt_pk_bf16(v[8 * j + 4] * rstd, v[8 * j + 5] * rstd); q.w = pg8::cvt_pk_bf16(v[8 * j + 6] * rstd, v[8 * j + 7] * rstd); *(LAS u32x4*)(T + s * 2080 + (64 * j + lane) * 16) = q; } }
.LBB0_307:
	v_readfirstlane_b32 s0, v66
	s_ashr_i32 s1, s0, 6
	s_lshl_b32 s0, s1, 1
	s_mul_i32 s3, s1, 0x1040
	v_lshl_or_b32 v14, s1, 3, v11
	s_ashr_i32 s1, s0, 31
	s_lshl_b64 s[10:11], s[0:1], 11
	s_add_u32 s10, s24, s10
	v_ashrrev_i32_e32 v15, 31, v14
	s_addc_u32 s11, s25, s11
	v_lshl_add_u32 v38, v14, 5, v12
	v_or_b32_e32 v26, 2, v14
	v_or_b32_e32 v28, 4, v14
	v_or_b32_e32 v30, 6, v14
	v_lshlrev_b64 v[32:33], 19, v[14:15]
	v_lshl_add_u64 v[14:15], s[10:11], 0, v[2:3]
	v_add_co_u32_e32 v22, vcc, s18, v14
	v_add_u32_e32 v13, s3, v10
	s_nop 0
	v_addc_co_u32_e32 v23, vcc, 0, v15, vcc
	global_load_dwordx4 v[14:17], v[22:23], off
	global_load_dwordx4 v[18:21], v[22:23], off offset:1024
	global_load_dwordx4 v[140:143], v[22:23], off offset:2048
	global_load_dwordx4 v[144:147], v[22:23], off offset:3072
	s_or_b32 s0, s0, 1
	s_mulk_i32 s0, 0x820
	v_lshl_add_u64 v[32:33], v[0:1], 0, v[32:33]
	v_lshl_add_u64 v[32:33], s[24:25], 0, v[32:33]
	s_add_i32 s2, s2, s12
	v_lshl_add_u64 v[2:3], v[2:3], 0, s[16:17]
	s_cmpk_lt_i32 s2, 0x400
	s_waitcnt vmcnt(0)
	v_and_b32_e32 v25, 0xffff0000, v14
	v_lshlrev_b32_e32 v24, 16, v14
	v_mul_f32_e32 v42, v25, v25
	v_lshlrev_b32_e32 v27, 16, v15
	v_fmac_f32_e32 v42, v24, v24
	v_and_b32_e32 v29, 0xffff0000, v15
	v_fmac_f32_e32 v42, v27, v27
	v_lshlrev_b32_e32 v31, 16, v16
	v_fmac_f32_e32 v42, v29, v29
	v_and_b32_e32 v34, 0xffff0000, v16
	v_fmac_f32_e32 v42, v31, v31
	v_lshlrev_b32_e32 v35, 16, v17
	v_fmac_f32_e32 v42, v34, v34
	v_and_b32_e32 v36, 0xffff0000, v17
	v_fmac_f32_e32 v42, v35, v35
	s_waitcnt vmcnt(0)
	v_lshlrev_b32_e32 v37, 16, v18
	v_fmac_f32_e32 v42, v36, v36
	v_and_b32_e32 v39, 0xffff0000, v18
	v_fmac_f32_e32 v42, v37, v37
	v_lshlrev_b32_e32 v40, 16, v19
	v_fmac_f32_e32 v42, v39, v39
	v_and_b32_e32 v41, 0xffff0000, v19
	v_and_b32_e32 v14, 0xffff0000, v20
	v_lshlrev_b32_e32 v15, 16, v20
	v_fmac_f32_e32 v42, v40, v40
	v_pk_mul_f32 v[18:19], v[14:15], v[14:15]
	v_fmac_f32_e32 v42, v41, v41
	v_and_b32_e32 v16, 0xffff0000, v21
	v_lshlrev_b32_e32 v17, 16, v21
	v_add_f32_e32 v19, v19, v42
	v_pk_mul_f32 v[20:21], v[16:17], v[16:17]
	v_add_f32_e32 v18, v18, v19
	v_add_f32_e32 v18, v21, v18
	v_add_f32_e32 v18, v20, v18
	ds_bpermute_b32 v19, v4, v18
	s_waitcnt lgkmcnt(0)
	v_add_f32_e32 v18, v18, v19
	ds_bpermute_b32 v19, v5, v18
	s_waitcnt lgkmcnt(0)
	v_add_f32_e32 v18, v18, v19
	ds_bpermute_b32 v19, v6, v18
	s_waitcnt lgkmcnt(0)
	v_add_f32_e32 v18, v18, v19
	ds_bpermute_b32 v19, v7, v18
	s_waitcnt lgkmcnt(0)
	v_add_f32_e32 v18, v18, v19
	ds_bpermute_b32 v19, v8, v18
	s_waitcnt lgkmcnt(0)
	v_add_f32_e32 v18, v18, v19
	ds_bpermute_b32 v19, v9, v18
	s_waitcnt lgkmcnt(0)
	v_add_f32_e32 v18, v18, v19
	v_fmamk_f32 v18, v18, 0x3a800000, v226
	v_mul_f32_e32 v19, 0x4b800000, v18
	v_cmp_gt_f32_e32 vcc, s5, v18
	s_nop 1
	v_cndmask_b32_e32 v18, v18, v19, vcc
	v_rsq_f32_e32 v18, v18
	s_nop 0
	v_mul_f32_e32 v19, 0x45800000, v18
	v_cndmask_b32_e32 v18, v18, v19, vcc
	v_mul_f32_e32 v19, v18, v24
	v_mul_f32_e32 v20, v18, v25
	v_mul_f32_e32 v21, v18, v27
	v_mul_f32_e32 v24, v18, v29
	v_mul_f32_e32 v25, v18, v31
	v_mul_f32_e32 v27, v18, v34
	v_mul_f32_e32 v29, v18, v35
	v_mul_f32_e32 v31, v18, v36
	v_mul_f32_e32 v34, v18, v37
	v_mul_f32_e32 v35, v18, v39
	v_mul_f32_e32 v36, v18, v40
	v_mul_f32_e32 v37, v18, v41
	v_mul_f32_e32 v39, v18, v15
	v_mul_f32_e32 v40, v18, v14
	v_mul_f32_e32 v41, v18, v17
	v_mul_f32_e32 v18, v18, v16
	v_cvt_pk_bf16_f32 v14, v19, v20
	v_cvt_pk_bf16_f32 v15, v21, v24
	v_cvt_pk_bf16_f32 v16, v25, v27
	v_cvt_pk_bf16_f32 v17, v29, v31
	ds_write_b128 v13, v[14:17]
	v_cvt_pk_bf16_f32 v14, v34, v35
	v_cvt_pk_bf16_f32 v15, v36, v37
	v_cvt_pk_bf16_f32 v16, v39, v40
	v_cvt_pk_bf16_f32 v17, v41, v18
	v_mov_b32_e32 v18, v140
	v_mov_b32_e32 v19, v141
	v_mov_b32_e32 v20, v142
	v_mov_b32_e32 v21, v143
	v_mov_b32_e32 v22, v144
	v_mov_b32_e32 v23, v145
	v_mov_b32_e32 v24, v146
	v_mov_b32_e32 v25, v147
	v_ashrrev_i32_e32 v27, 31, v26
	v_lshl_add_u32 v39, v26, 5, v12
	v_lshlrev_b64 v[26:27], 19, v[26:27]
	v_ashrrev_i32_e32 v29, 31, v28
	v_lshl_add_u64 v[26:27], v[0:1], 0, v[26:27]
	v_lshl_add_u32 v40, v28, 5, v12
	v_lshlrev_b64 v[28:29], 19, v[28:29]
	v_lshl_add_u64 v[34:35], s[24:25], 0, v[26:27]
	v_lshl_add_u64 v[28:29], v[0:1], 0, v[28:29]
	ds_write_b128 v13, v[14:17] offset:1024
	v_lshl_add_u64 v[36:37], s[24:25], 0, v[28:29]
	v_add_u32_e32 v26, s0, v10
	v_lshl_add_u32 v41, v30, 5, v12
	v_ashrrev_i32_e32 v31, 31, v30
	v_lshlrev_b64 v[30:31], 19, v[30:31]
	v_lshl_add_u64 v[30:31], v[0:1], 0, v[30:31]
	v_lshl_add_u64 v[30:31], s[24:25], 0, v[30:31]
	v_lshl_add_u64 v[0:1], v[0:1], 0, s[14:15]
	s_waitcnt vmcnt(1)
; __device__ __forceinline__ unsigned cvt_pk_bf16(float lo, float hi) { unsigned r; asm volatile("v_cvt_pk_bf16_f32 %0, %1, %2" : "=v"(r) : "v"(lo), "v"(hi)); return r; }
; #define LAS __attribute__((address_space(3)))
; #define LDS_WAIT() asm volatile("s_waitcnt lgkmcnt(0)" ::: "memory")
; template <bool F32SRC> __device__ __forceinline__ void unorm_chunk(LAS unsigned char* lds, const float* xsrc, bf16_t* hbio, bf16_t* Ug, int chunk, const int tid) {
;     ...
;         } else { const u32x4* xr = (const u32x4*)(hbio + row * DM) + lane; u32x4 w[2]; float v[16]; float ss = 0.f;
; #pragma unroll
;             for (int j = 0; j < 2; ++j) { w[j] = xr[64 * j];
;                 v[8 * j + 0] = __uint_as_float(w[j].x << 16); v[8 * j + 1] = __uint_as_float(w[j].x & 0xffff0000u); v[8 * j + 2] = __uint_as_float(w[j].y << 16); v[8 * j + 3] = __uint_as_float(w[j].y & 0xffff0000u);
;                 v[8 * j + 4] = __uint_as_float(w[j].z << 16); v[8 * j + 5] = __uint_as_float(w[j].z & 0xffff0000u); v[8 * j + 6] = __uint_as_float(w[j].w << 16); v[8 * j + 7] = __uint_as_float(w[j].w & 0xffff0000u); }
; #pragma unroll
;             for (int i = 0; i < 16; ++i) ss += v[i] * v[i];
;             const float rstd = rsqrtf(wsum_l(ss, lane) * (1.0f / DM) + EPS);
; #pragma unroll
;             for (int j = 0; j < 2; ++j) { u32x4 q; q.x = pg8::cvt_pk_bf16(v[8 * j] * rstd, v[8 * j + 1] * rstd); q.y = pg8::cvt_pk_bf16(v[8 * j + 2] * rstd, v[8 * j + 3] * rstd);
;                 q.z = pg8::cvt_pk_bf16(v[8 * j + 4] * rstd, v[8 * j + 5] * rstd); q.w = pg8::cvt_pk_bf16(v[8 * j + 6] * rstd, v[8 * j + 7] * rstd); *(LAS u32x4*)(T + s * 2080 + (64 * j + lane) * 16) = q; } }
;     }
;     LDS_WAIT(); __syncthreads();
; #pragma unroll
;     for (int i = 0; i < 4; ++i) { const int gq = 8 * wid + 2 * i + (lane >> 5), l = lane & 31, s = l >> 1, hf = l & 1;
;         const u32x4 q = *(const LAS u32x4*)(T + s * 2080 + gq * 32 + hf * 16);
;         *(u32x4*)(Ug + ((size_t)gq * 1024 + chunk) * 256 + l * 8) = q; }
;     LDS_WAIT(); __syncthreads();
	v_and_b32_e32 v27, 0xffff0000, v18
	v_lshlrev_b32_e32 v13, 16, v18
	s_waitcnt vmcnt(0)
	v_and_b32_e32 v14, 0xffff0000, v24
	v_lshlrev_b32_e32 v15, 16, v24
	v_mul_f32_e32 v24, v27, v27
	v_lshlrev_b32_e32 v28, 16, v19
	v_fmac_f32_e32 v24, v13, v13
	v_and_b32_e32 v29, 0xffff0000, v19
	v_fmac_f32_e32 v24, v28, v28
	v_lshlrev_b32_e32 v42, 16, v20
	v_fmac_f32_e32 v24, v29, v29
	v_and_b32_e32 v43, 0xffff0000, v20
	v_fmac_f32_e32 v24, v42, v42
	v_lshlrev_b32_e32 v44, 16, v21
	v_fmac_f32_e32 v24, v43, v43
	v_and_b32_e32 v45, 0xffff0000, v21
	v_fmac_f32_e32 v24, v44, v44
	v_lshlrev_b32_e32 v46, 16, v22
	v_fmac_f32_e32 v24, v45, v45
	v_and_b32_e32 v22, 0xffff0000, v22
	v_fmac_f32_e32 v24, v46, v46
	v_lshlrev_b32_e32 v47, 16, v23
	v_fmac_f32_e32 v24, v22, v22
	v_and_b32_e32 v23, 0xffff0000, v23
	v_fmac_f32_e32 v24, v47, v47
	v_pk_mul_f32 v[18:19], v[14:15], v[14:15]
	v_fmac_f32_e32 v24, v23, v23
	v_and_b32_e32 v16, 0xffff0000, v25
	v_lshlrev_b32_e32 v17, 16, v25
	v_add_f32_e32 v19, v19, v24
	v_pk_mul_f32 v[20:21], v[16:17], v[16:17]
	v_add_f32_e32 v18, v18, v19
	v_add_f32_e32 v18, v21, v18
	v_add_f32_e32 v18, v20, v18
	ds_bpermute_b32 v19, v4, v18
	s_waitcnt lgkmcnt(0)
	v_add_f32_e32 v18, v18, v19
	ds_bpermute_b32 v19, v5, v18
	s_waitcnt lgkmcnt(0)
	v_add_f32_e32 v18, v18, v19
	ds_bpermute_b32 v19, v6, v18
	s_waitcnt lgkmcnt(0)
	v_add_f32_e32 v18, v18, v19
	ds_bpermute_b32 v19, v7, v18
	s_waitcnt lgkmcnt(0)
	v_add_f32_e32 v18, v18, v19
	ds_bpermute_b32 v19, v8, v18
	s_waitcnt lgkmcnt(0)
	v_add_f32_e32 v18, v18, v19
	ds_bpermute_b32 v19, v9, v18
	s_waitcnt lgkmcnt(0)
	v_add_f32_e32 v18, v18, v19
	v_fmamk_f32 v18, v18, 0x3a800000, v226
	v_mul_f32_e32 v19, 0x4b800000, v18
	v_cmp_gt_f32_e32 vcc, s5, v18
	s_nop 1
	v_cndmask_b32_e32 v18, v18, v19, vcc
	v_rsq_f32_e32 v18, v18
	s_nop 0
	v_mul_f32_e32 v19, 0x45800000, v18
	v_cndmask_b32_e32 v18, v18, v19, vcc
	v_mul_f32_e32 v13, v18, v13
	v_mul_f32_e32 v19, v18, v27
	v_mul_f32_e32 v20, v18, v28
	v_mul_f32_e32 v21, v18, v29
	v_mul_f32_e32 v24, v18, v42
	v_mul_f32_e32 v25, v18, v43
	v_mul_f32_e32 v27, v18, v44
	v_mul_f32_e32 v28, v18, v45
	v_mul_f32_e32 v29, v18, v46
	v_mul_f32_e32 v22, v18, v22
	v_mul_f32_e32 v42, v18, v47
	v_mul_f32_e32 v23, v18, v23
	v_mul_f32_e32 v43, v18, v15
	v_mul_f32_e32 v44, v18, v14
	v_mul_f32_e32 v45, v18, v17
	v_mul_f32_e32 v18, v18, v16
	v_cvt_pk_bf16_f32 v14, v13, v19
	v_cvt_pk_bf16_f32 v15, v20, v21
	v_cvt_pk_bf16_f32 v16, v24, v25
	v_cvt_pk_bf16_f32 v17, v27, v28
	ds_write_b128 v26, v[14:17]
	v_cvt_pk_bf16_f32 v14, v29, v22
	v_cvt_pk_bf16_f32 v15, v42, v23
	v_cvt_pk_bf16_f32 v16, v43, v44
	v_cvt_pk_bf16_f32 v17, v45, v18
	ds_write_b128 v26, v[14:17] offset:1024
	s_waitcnt lgkmcnt(0)
	s_waitcnt lgkmcnt(0)
	s_barrier
	ds_read_b128 v[14:17], v38
	ds_read_b128 v[18:21], v39
	ds_read_b128 v[22:25], v40
	ds_read_b128 v[26:29], v41
	s_waitcnt lgkmcnt(3)
	global_store_dwordx4 v[32:33], v[14:17], off
	s_waitcnt lgkmcnt(2)
	global_store_dwordx4 v[34:35], v[18:21], off
	s_waitcnt lgkmcnt(1)
	global_store_dwordx4 v[36:37], v[22:25], off
	s_waitcnt lgkmcnt(0)
	global_store_dwordx4 v[30:31], v[26:29], off
	s_waitcnt lgkmcnt(0)
	s_barrier
	s_cbranch_scc1 .LBB0_307

; __device__ __forceinline__ unsigned cvt_pk_bf16(float lo, float hi) { unsigned r; asm volatile("v_cvt_pk_bf16_f32 %0, %1, %2" : "=v"(r) : "v"(lo), "v"(hi)); return r; }
; #define LAS __attribute__((address_space(3)))
; template <bool F32SRC> __device__ __forceinline__ void unorm_chunk(LAS unsigned char* lds, const float* xsrc, bf16_t* hbio, bf16_t* Ug, int chunk, const int tid) {
;     ...
;     for (int rr = 0; rr < 2; ++rr) { const int s = 2 * wid + rr; const size_t row = (size_t)chunk * 16 + s;
;         if (F32SRC) { const f32x4* xr = (const f32x4*)(xsrc + row * DM) + lane; f32x4 v[4]; float ss = 0.f;
; #pragma unroll
;             for (int j = 0; j < 4; ++j) { v[j] = __builtin_nontemporal_load(xr + 64 * j); ss += (v[j].x * v[j].x + v[j].y * v[j].y) + (v[j].z * v[j].z + v[j].w * v[j].w); }
;             const float rstd = rsqrtf(wsum_l(ss, lane) * (1.0f / DM) + EPS);
;             u32x2* o = (u32x2*)(hbio + row * DM) + lane;
; #pragma unroll
;             for (int j = 0; j < 4; ++j) { u32x2 w; w.x = pg8::cvt_pk_bf16(v[j].x, v[j].y); w.y = pg8::cvt_pk_bf16(v[j].z, v[j].w); o[64 * j] = w;
;                 u32x2 q; q.x = pg8::cvt_pk_bf16(v[j].x * rstd, v[j].y * rstd); q.y = pg8::cvt_pk_bf16(v[j].z * rstd, v[j].w * rstd); *(LAS u32x2*)(T + s * 2080 + (64 * j + lane) * 8) = q; }
.LBB0_312:
	ds_read_b64 v[6:7], v236
	ds_read_b64 v[8:9], v236
	v_readfirstlane_b32 s0, v66
	s_ashr_i32 s1, s0, 6
	s_lshl_b32 s0, s1, 1
	s_mul_i32 s3, s1, 0x1040
	s_mov_b32 s2, s97
	v_lshl_or_b32 v20, s1, 3, v16
	s_ashr_i32 s1, s0, 31
	v_add_u32_e32 v19, s3, v18
	s_waitcnt lgkmcnt(0)
	v_readfirstlane_b32 s3, v7
	s_waitcnt lgkmcnt(0)
	v_readfirstlane_b32 s96, v8
	s_lshl_b64 s[10:11], s[0:1], 12
	s_or_b64 s[2:3], s[96:97], s[2:3]
	s_add_u32 s2, s2, s10
	v_ashrrev_i32_e32 v21, 31, v20
	v_or_b32_e32 v22, 2, v20
	s_addc_u32 s3, s3, s11
	v_lshl_add_u32 v60, v20, 5, v17
	v_or_b32_e32 v32, 4, v20
	v_or_b32_e32 v34, 6, v20
	v_lshlrev_b64 v[20:21], 19, v[20:21]
	v_ashrrev_i32_e32 v23, 31, v22
	v_lshl_add_u64 v[40:41], s[2:3], 0, v[2:3]
	v_lshl_add_u32 v61, v22, 5, v17
	v_lshl_add_u64 v[36:37], v[0:1], 0, v[20:21]
	v_lshlrev_b64 v[38:39], 19, v[22:23]
	global_load_dwordx4 v[6:9], v[40:41], off nt
	global_load_dwordx4 v[20:23], v[40:41], off offset:1024 nt
	global_load_dwordx4 v[24:27], v[40:41], off offset:3072 nt
	global_load_dwordx4 v[28:31], v[40:41], off offset:2048 nt
	s_lshl_b64 s[10:11], s[0:1], 11
	s_add_u32 s2, s38, s10
	s_addc_u32 s3, s39, s11
	v_add_co_u32_e32 v40, vcc, s13, v40
	v_lshl_add_u64 v[42:43], s[2:3], 0, v[4:5]
	s_nop 0
	v_addc_co_u32_e32 v41, vcc, 0, v41, vcc
	s_nop 0
	global_load_dwordx4 v[140:143], v[40:41], off nt
	global_load_dwordx4 v[144:147], v[40:41], off offset:1024 nt
	global_load_dwordx4 v[148:151], v[40:41], off offset:2048 nt
	global_load_dwordx4 v[152:155], v[40:41], off offset:3072 nt
	v_add_co_u32_e32 v42, vcc, s21, v42
	s_or_b32 s0, s0, 1
	s_nop 0
	v_addc_co_u32_e32 v43, vcc, 0, v43, vcc
	s_mulk_i32 s0, 0x820
	v_lshl_add_u32 v62, v32, 5, v17
	v_lshl_add_u32 v63, v34, 5, v17
	v_ashrrev_i32_e32 v33, 31, v32
	v_ashrrev_i32_e32 v35, 31, v34
	v_lshlrev_b64 v[32:33], 19, v[32:33]
	v_lshlrev_b64 v[34:35], 19, v[34:35]
	v_lshl_add_u64 v[36:37], s[38:39], 0, v[36:37]
	v_lshl_add_u64 v[38:39], v[0:1], 0, v[38:39]
	v_lshl_add_u64 v[32:33], v[0:1], 0, v[32:33]
	v_lshl_add_u64 v[34:35], v[0:1], 0, v[34:35]
	v_lshl_add_u64 v[38:39], s[38:39], 0, v[38:39]
	v_lshl_add_u64 v[32:33], s[38:39], 0, v[32:33]
	v_lshl_add_u64 v[34:35], s[38:39], 0, v[34:35]
	s_add_i32 s5, s5, s12
	v_lshl_add_u64 v[0:1], v[0:1], 0, s[14:15]
	v_lshl_add_u64 v[2:3], v[2:3], 0, s[18:19]
	v_lshl_add_u64 v[4:5], v[4:5], 0, s[16:17]
	s_cmpk_gt_i32 s5, 0x3ff
	s_waitcnt vmcnt(0)
	v_cvt_pk_bf16_f32 v56, v6, v7
	v_pk_mul_f32 v[44:45], v[8:9], v[8:9]
	v_pk_mul_f32 v[46:47], v[6:7], v[6:7]
	s_waitcnt vmcnt(2)
	v_pk_mul_f32 v[48:49], v[22:23], v[22:23]
	v_pk_mul_f32 v[50:51], v[20:21], v[20:21]
	v_pk_mov_b32 v[58:59], v[46:47], v[44:45] op_sel:[1,0]
	v_mov_b32_e32 v47, v45
	v_pk_mov_b32 v[44:45], v[50:51], v[48:49] op_sel:[1,0]
	v_mov_b32_e32 v51, v49
	s_waitcnt vmcnt(1)
	v_mul_f32_e32 v55, v24, v24
	s_waitcnt vmcnt(0)
	v_mul_f32_e32 v52, v29, v29
	v_mul_f32_e32 v54, v31, v31
	v_pk_add_f32 v[46:47], v[58:59], v[46:47]
	v_pk_add_f32 v[44:45], v[44:45], v[50:51]
	v_mul_f32_e32 v67, v25, v25
	v_mul_f32_e32 v68, v26, v26
	v_mul_f32_e32 v69, v27, v27
	v_pk_fma_f32 v[48:49], v[28:29], v[28:29], v[52:53] op_sel_hi:[1,1,0]
	v_pk_fma_f32 v[52:53], v[30:31], v[30:31], v[54:55] op_sel_hi:[1,1,0]
	v_pk_add_f32 v[46:47], v[46:47], v[46:47] op_sel:[0,1] op_sel_hi:[1,0]
	v_pk_add_f32 v[44:45], v[44:45], v[44:45] op_sel:[0,1] op_sel_hi:[1,0]
	v_mov_b32_e32 v49, v68
	v_mov_b32_e32 v53, v69
	v_mov_b32_e32 v47, v55
	v_mov_b32_e32 v45, v67
	v_pk_add_f32 v[48:49], v[48:49], v[52:53]
	v_pk_add_f32 v[44:45], v[46:47], v[44:45]
	v_cvt_pk_bf16_f32 v57, v8, v9
	global_store_dwordx2 v[42:43], v[56:57], off
	v_pk_add_f32 v[44:45], v[44:45], v[48:49]
	s_nop 0
	v_add_f32_e32 v44, v44, v45
	ds_bpermute_b32 v45, v10, v44
	s_waitcnt lgkmcnt(0)
	v_add_f32_e32 v44, v44, v45
	ds_bpermute_b32 v45, v11, v44
	s_waitcnt lgkmcnt(0)
	v_add_f32_e32 v44, v44, v45
	ds_bpermute_b32 v45, v12, v44
	s_waitcnt lgkmcnt(0)
	v_add_f32_e32 v44, v44, v45
	ds_bpermute_b32 v45, v13, v44
	s_waitcnt lgkmcnt(0)
	v_add_f32_e32 v44, v44, v45
	ds_bpermute_b32 v45, v14, v44
	s_waitcnt lgkmcnt(0)
	v_add_f32_e32 v44, v44, v45
	ds_bpermute_b32 v45, v15, v44
	s_waitcnt lgkmcnt(0)
; #define LAS __attribute__((address_space(3)))
; template <bool F32SRC> __device__ __forceinline__ void unorm_chunk(LAS unsigned char* lds, const float* xsrc, bf16_t* hbio, bf16_t* Ug, int chunk, const int tid) {
;     ...
;     for (int rr = 0; rr < 2; ++rr) { const int s = 2 * wid + rr; const size_t row = (size_t)chunk * 16 + s;
;         if (F32SRC) { const f32x4* xr = (const f32x4*)(xsrc + row * DM) + lane; f32x4 v[4]; float ss = 0.f;
; #pragma unroll
;             for (int j = 0; j < 4; ++j) { v[j] = __builtin_nontemporal_load(xr + 64 * j); ss += (v[j].x * v[j].x + v[j].y * v[j].y) + (v[j].z * v[j].z + v[j].w * v[j].w); }
;             const float rstd = rsqrtf(wsum_l(ss, lane) * (1.0f / DM) + EPS);
;             u32x2* o = (u32x2*)(hbio + row * DM) + lane;
; #pragma unroll
;             for (int j = 0; j < 4; ++j) { u32x2 w; w.x = pg8::cvt_pk_bf16(v[j].x, v[j].y); w.y = pg8::cvt_pk_bf16(v[j].z, v[j].w); o[64 * j] = w;
;                 u32x2 q; q.x = pg8::cvt_pk_bf16(v[j].x * rstd, v[j].y * rstd); q.y = pg8::cvt_pk_bf16(v[j].z * rstd, v[j].w * rstd); *(LAS u32x2*)(T + s * 2080 + (64 * j + lane) * 8) = q; }
;         } else { const u32x4* xr = (const u32x4*)(hbio + row * DM) + lane; u32x4 w[2]; float v[16]; float ss = 0.f;
; #pragma unroll
;             for (int j = 0; j < 2; ++j) { w[j] = xr[64 * j];
;                 v[8 * j + 0] = __uint_as_float(w[j].x << 16); v[8 * j + 1] = __uint_as_float(w[j].x & 0xffff0000u); v[8 * j + 2] = __uint_as_float(w[j].y << 16); v[8 * j + 3] = __uint_as_float(w[j].y & 0xffff0000u);
;                 v[8 * j + 4] = __uint_as_float(w[j].z << 16); v[8 * j + 5] = __uint_as_float(w[j].z & 0xffff0000u); v[8 * j + 6] = __uint_as_float(w[j].w << 16); v[8 * j + 7] = __uint_as_float(w[j].w & 0xffff0000u); }
; #pragma unroll
;             for (int i = 0; i < 16; ++i) ss += v[i] * v[i];
;             const float rstd = rsqrtf(wsum_l(ss, lane) * (1.0f / DM) + EPS);
; #pragma unroll
;             for (int j = 0; j < 2; ++j) { u32x4 q; q.x = pg8::cvt_pk_bf16(v[8 * j] * rstd, v[8 * j + 1] * rstd); q.y = pg8::cvt_pk_bf16(v[8 * j + 2] * rstd, v[8 * j + 3] * rstd);
;                 q.z = pg8::cvt_pk_bf16(v[8 * j + 4] * rstd, v[8 * j + 5] * rstd); q.w = pg8::cvt_pk_bf16(v[8 * j + 6] * rstd, v[8 * j + 7] * rstd); *(LAS u32x4*)(T + s * 2080 + (64 * j + lane) * 16) = q; } }
;     }
;     LDS_WAIT(); __syncthreads();
; #pragma unroll
	v_add_f32_e32 v44, v44, v45
	v_fmamk_f32 v44, v44, 0x3a800000, v226
	v_mul_f32_e32 v45, 0x4b800000, v44
	v_cmp_gt_f32_e32 vcc, s24, v44
	s_nop 1
	v_cndmask_b32_e32 v44, v44, v45, vcc
	v_rsq_f32_e32 v44, v44
	s_nop 0
	v_mul_f32_e32 v45, 0x45800000, v44
	v_cndmask_b32_e32 v44, v44, v45, vcc
	v_mul_f32_e32 v6, v6, v44
	v_mul_f32_e32 v7, v7, v44
	v_mul_f32_e32 v8, v8, v44
	v_mul_f32_e32 v9, v9, v44
	v_cvt_pk_bf16_f32 v6, v6, v7
	v_cvt_pk_bf16_f32 v7, v8, v9
	ds_write_b64 v19, v[6:7]
	v_cvt_pk_bf16_f32 v6, v20, v21
	v_cvt_pk_bf16_f32 v7, v22, v23
	v_mul_f32_e32 v45, v20, v44
	v_mul_f32_e32 v46, v21, v44
	v_mul_f32_e32 v47, v22, v44
	v_mul_f32_e32 v48, v23, v44
	global_store_dwordx2 v[42:43], v[6:7], off offset:512
	v_cvt_pk_bf16_f32 v6, v45, v46
	v_cvt_pk_bf16_f32 v7, v47, v48
	ds_write_b64 v19, v[6:7] offset:512
	v_cvt_pk_bf16_f32 v6, v28, v29
	v_cvt_pk_bf16_f32 v7, v30, v31
	v_mul_f32_e32 v49, v28, v44
	v_mul_f32_e32 v50, v29, v44
	v_mul_f32_e32 v51, v30, v44
	v_mul_f32_e32 v52, v31, v44
	global_store_dwordx2 v[42:43], v[6:7], off offset:1024
	v_cvt_pk_bf16_f32 v6, v49, v50
	v_cvt_pk_bf16_f32 v7, v51, v52
	ds_write_b64 v19, v[6:7] offset:1024
	v_cvt_pk_bf16_f32 v6, v24, v25
	v_cvt_pk_bf16_f32 v7, v26, v27
	v_mul_f32_e32 v53, v24, v44
	v_mul_f32_e32 v54, v25, v44
	v_mul_f32_e32 v55, v26, v44
	v_mul_f32_e32 v56, v27, v44
	global_store_dwordx2 v[42:43], v[6:7], off offset:1536
	v_cvt_pk_bf16_f32 v44, v53, v54
	v_cvt_pk_bf16_f32 v45, v55, v56
	v_mov_b32_e32 v6, v140
	v_mov_b32_e32 v7, v141
	v_mov_b32_e32 v8, v142
	v_mov_b32_e32 v9, v143
	v_mov_b32_e32 v20, v144
	v_mov_b32_e32 v21, v145
	v_mov_b32_e32 v22, v146
	v_mov_b32_e32 v23, v147
	v_mov_b32_e32 v24, v148
	v_mov_b32_e32 v25, v149
	v_mov_b32_e32 v26, v150
	v_mov_b32_e32 v27, v151
	v_mov_b32_e32 v28, v152
	v_mov_b32_e32 v29, v153
	v_mov_b32_e32 v30, v154
	v_mov_b32_e32 v31, v155
	ds_write_b64 v19, v[44:45] offset:1536
	v_add_u32_e32 v53, s0, v18
	s_waitcnt vmcnt(3)
	v_cvt_pk_bf16_f32 v54, v6, v7
	v_pk_mul_f32 v[40:41], v[8:9], v[8:9]
	v_pk_mul_f32 v[44:45], v[6:7], v[6:7]
	s_waitcnt vmcnt(2)
	v_pk_mul_f32 v[46:47], v[22:23], v[22:23]
	v_pk_mul_f32 v[48:49], v[20:21], v[20:21]
	v_pk_mov_b32 v[56:57], v[44:45], v[40:41] op_sel:[1,0]
	v_mov_b32_e32 v45, v41
	v_pk_mov_b32 v[40:41], v[48:49], v[46:47] op_sel:[1,0]
	v_mov_b32_e32 v49, v47
	s_waitcnt vmcnt(1)
	v_mul_f32_e32 v50, v25, v25
	v_mul_f32_e32 v52, v27, v27
	v_pk_add_f32 v[44:45], v[56:57], v[44:45]
	v_pk_add_f32 v[40:41], v[40:41], v[48:49]
	s_waitcnt vmcnt(0)
	v_mul_f32_e32 v19, v28, v28
	v_mul_f32_e32 v58, v29, v29
	v_mul_f32_e32 v59, v30, v30
	v_mul_f32_e32 v67, v31, v31
	v_pk_fma_f32 v[46:47], v[24:25], v[24:25], v[50:51] op_sel_hi:[1,1,0]
	v_pk_fma_f32 v[50:51], v[26:27], v[26:27], v[52:53] op_sel_hi:[1,1,0]
	v_pk_add_f32 v[44:45], v[44:45], v[44:45] op_sel:[0,1] op_sel_hi:[1,0]
	v_pk_add_f32 v[40:41], v[40:41], v[40:41] op_sel:[0,1] op_sel_hi:[1,0]
	v_mov_b32_e32 v47, v59
	v_mov_b32_e32 v51, v67
	v_mov_b32_e32 v45, v19
	v_mov_b32_e32 v41, v58
	v_pk_add_f32 v[46:47], v[46:47], v[50:51]
	v_pk_add_f32 v[40:41], v[44:45], v[40:41]
	v_cvt_pk_bf16_f32 v55, v8, v9
	global_store_dwordx2 v[42:43], v[54:55], off offset:2048
	v_pk_add_f32 v[40:41], v[40:41], v[46:47]
	s_nop 0
	v_add_f32_e32 v19, v40, v41
	ds_bpermute_b32 v40, v10, v19
	s_waitcnt lgkmcnt(0)
	v_add_f32_e32 v19, v19, v40
	ds_bpermute_b32 v40, v11, v19
	s_waitcnt lgkmcnt(0)
	v_add_f32_e32 v19, v19, v40
	ds_bpermute_b32 v40, v12, v19
	s_waitcnt lgkmcnt(0)
	v_add_f32_e32 v19, v19, v40
	ds_bpermute_b32 v40, v13, v19
	s_waitcnt lgkmcnt(0)
	v_add_f32_e32 v19, v19, v40
	ds_bpermute_b32 v40, v14, v19
	s_waitcnt lgkmcnt(0)
	v_add_f32_e32 v19, v19, v40
	ds_bpermute_b32 v40, v15, v19
	s_waitcnt lgkmcnt(0)
	v_add_f32_e32 v19, v19, v40
	v_fmamk_f32 v19, v19, 0x3a800000, v226
	v_mul_f32_e32 v40, 0x4b800000, v19
	v_cmp_gt_f32_e32 vcc, s24, v19
	s_nop 1
	v_cndmask_b32_e32 v19, v19, v40, vcc
	v_rsq_f32_e32 v19, v19
	s_nop 0
	v_mul_f32_e32 v40, 0x45800000, v19
	v_cndmask_b32_e32 v19, v19, v40, vcc
	v_mul_f32_e32 v6, v6, v19
	v_mul_f32_e32 v7, v7, v19
	v_mul_f32_e32 v8, v8, v19
	v_mul_f32_e32 v9, v9, v19
	v_cvt_pk_bf16_f32 v6, v6, v7
	v_cvt_pk_bf16_f32 v7, v8, v9
	ds_write_b64 v53, v[6:7]
	v_cvt_pk_bf16_f32 v6, v20, v21
	v_cvt_pk_bf16_f32 v7, v22, v23
	v_mul_f32_e32 v40, v20, v19
	v_mul_f32_e32 v41, v21, v19
	v_mul_f32_e32 v44, v22, v19
	v_mul_f32_e32 v45, v23, v19
	global_store_dwordx2 v[42:43], v[6:7], off offset:2560
	v_cvt_pk_bf16_f32 v6, v40, v41
	v_cvt_pk_bf16_f32 v7, v44, v45
	ds_write_b64 v53, v[6:7] offset:512
	v_cvt_pk_bf16_f32 v6, v24, v25
	v_cvt_pk_bf16_f32 v7, v26, v27
	v_mul_f32_e32 v46, v24, v19
	v_mul_f32_e32 v47, v25, v19
	v_mul_f32_e32 v48, v26, v19
	v_mul_f32_e32 v49, v27, v19
	global_store_dwordx2 v[42:43], v[6:7], off offset:3072
	v_cvt_pk_bf16_f32 v6, v46, v47
	v_cvt_pk_bf16_f32 v7, v48, v49
	ds_write_b64 v53, v[6:7] offset:1024
	v_cvt_pk_bf16_f32 v6, v28, v29
	v_cvt_pk_bf16_f32 v7, v30, v31
	v_mul_f32_e32 v50, v28, v19
	v_mul_f32_e32 v51, v29, v19
	v_mul_f32_e32 v52, v30, v19
	v_mul_f32_e32 v19, v31, v19
	global_store_dwordx2 v[42:43], v[6:7], off offset:3584
	v_cvt_pk_bf16_f32 v6, v50, v51
	v_cvt_pk_bf16_f32 v7, v52, v19
	ds_write_b64 v53, v[6:7] offset:1536
	s_waitcnt lgkmcnt(0)
	s_waitcnt lgkmcnt(0)
	s_barrier
	ds_read_b128 v[6:9], v60
	ds_read_b128 v[20:23], v61
	ds_read_b128 v[24:27], v62
	ds_read_b128 v[28:31], v63
	s_waitcnt lgkmcnt(3)
	global_store_dwordx4 v[36:37], v[6:9], off
	s_waitcnt lgkmcnt(2)
	global_store_dwordx4 v[38:39], v[20:23], off
	s_waitcnt lgkmcnt(1)
	global_store_dwordx4 v[32:33], v[24:27], off
	s_waitcnt lgkmcnt(0)
	global_store_dwordx4 v[34:35], v[28:31], off
	s_waitcnt lgkmcnt(0)
	s_barrier
	s_cbranch_scc0 .LBB0_312
